# plus up-projection GEMM epilogue (conv3 + gelu + gate) rewritten by hand: conv taps by v_fmac_f32_dpp on the accumulators, same gelu op sequence, about half the VALU instructions of the compiled epilo
# speedup vs baseline: 1.0269x; 1.0190x over previous
;     __device__ __forceinline__ void operator()(const f32x4 (&acc)[2][2][4][2], const Unit& u, int wr, int wc, int fr, int fq) const {
;         const int cl = wc * 32 + 8 * fq, cgc = u.pn * 128 + cl; const bool samp = u.pm >= 64;
;         f32x4 cw0[2], cw1[2], cw2[2], cb[2];
; #pragma unroll
;         for (int n = 0; n < 2; ++n) { cw0[n] = *(const f32x4*)(conv_w + cgc + 4 * n); cw1[n] = *(const f32x4*)(conv_w + DFF + cgc + 4 * n); cw2[n] = *(const f32x4*)(conv_w + 2 * DFF + cgc + 4 * n); cb[n] = *(const f32x4*)(conv_b + cgc + 4 * n); }
;         if (!samp) {
;             if (fr >= 14) {
; #pragma unroll
;                 for (int ai = 0; ai < 2; ++ai)
; #pragma unroll
;                     for (int n = 0; n < 2; ++n) *(PG8_LAS f32x4*)(xbuf + ((ai * 2 + wr) * 2 + (fr - 14)) * 128 + cl + 4 * n) = acc[ai][0][3][n];
;             }
;             asm volatile("s_waitcnt lgkmcnt(0)" ::: "memory"); __builtin_amdgcn_s_barrier(); asm volatile("" ::: "memory");
;         }
; #pragma unroll
;         for (int ai = 0; ai < 2; ++ai) { const int blk = ai * 2 + wr;
; #pragma unroll
;             for (int m = 0; m < 4; ++m) {
;                 const int row = u.pm * BM + ai * HALF + wr * 64 + m * 16 + fr;
;                 f32x4 w1[2], w2[2];
;                 if (samp) {
;                     const int bs = (row - MP) >> 4;
; #pragma unroll
;                     for (int n = 0; n < 2; ++n) { const f32x4 s0 = *(const f32x4*)(state + ((size_t)bs * 2 + 0) * DFF + cgc + 4 * n), s1 = *(const f32x4*)(state + ((size_t)bs * 2 + 1) * DFF + cgc + 4 * n);
;                         w1[n] = s1; w2[n] = fr == 0 ? s0 : s1; }
;                 } else if (m == 0) {
;                     if (blk > 0) {
; #pragma unroll
;                         for (int n = 0; n < 2; ++n) { const f32x4 c14 = *(const PG8_LAS f32x4*)(xbuf + ((blk - 1) * 2 + 0) * 128 + cl + 4 * n), c15 = *(const PG8_LAS f32x4*)(xbuf + ((blk - 1) * 2 + 1) * 128 + cl + 4 * n);
;                             w1[n] = c15; w2[n] = fr == 0 ? c14 : c15; }
;                     } else { w1[0] = w1[1] = w2[0] = w2[1] = (f32x4){0.f, 0.f, 0.f, 0.f}; }
;     ...
;                 f32x4 hv[2];
; #pragma unroll
;                 for (int n = 0; n < 2; ++n) {
;                     const f32x4 a = acc[ai][0][m][n], b = acc[ai][1][m][n];
; #pragma unroll
;                     for (int i = 0; i < 4; ++i) {
.LBB0_1229:
	s_mov_b32 s56, s22
	s_mov_b32 s57, s67
	v_readlane_b32 s58, v251, 21
	v_readlane_b32 s76, v251, 26
	v_readlane_b32 s77, v251, 27
	v_readlane_b32 s78, v250, 4
	v_readlane_b32 s79, v250, 5
	v_readlane_b32 s60, v251, 46
	v_readlane_b32 s61, v251, 47
	v_readlane_b32 s66, v251, 62
	v_readlane_b32 s67, v251, 63
	v_bfe_u32 v214, v1, 4, 2
	v_bfe_u32 v215, v1, 6, 2
	v_lshlrev_b32_e32 v214, 3, v214
	v_lshl_add_u32 v214, v215, 5, v214
	v_and_b32_e32 v216, 15, v1
	v_and_b32_e32 v217, 1, v1
	s_lshr_b32 s58, s58, 2
	v_lshl_add_u32 v194, s57, 7, v214
	v_lshlrev_b32_e32 v194, 2, v194
	v_lshl_add_u32 v196, v217, 15, v194
	s_lshl_b32 s59, s56, 8
	s_lshl_b32 s31, s58, 6
	s_add_u32 s59, s59, s31
	v_add_u32_e32 v218, s59, v216
	v_lshlrev_b32_e32 v195, 14, v218
	v_lshrrev_b32_e32 v219, 1, v194
	v_add_u32_e32 v195, v195, v219
	v_lshlrev_b32_e32 v197, 9, v217
	v_lshl_add_u32 v197, v214, 2, v197
	s_lshl_b32 s31, s58, 10
	s_add_u32 s31, s31, 0x20000
	v_add_u32_e32 v197, s31, v197
	s_add_u32 s62, s60, 0x8000
	s_addc_u32 s63, s61, 0
	s_add_u32 s64, s60, 0x10000
	s_addc_u32 s65, s61, 0
	s_add_u32 s70, s76, 0xdb00000
	s_addc_u32 s71, s77, 0
	global_load_dwordx4 v[42:45], v194, s[60:61]
	global_load_dwordx4 v[46:49], v194, s[60:61] offset:16
	global_load_dwordx4 v[50:53], v194, s[62:63]
	global_load_dwordx4 v[54:57], v194, s[62:63] offset:16
	global_load_dwordx4 v[66:69], v194, s[64:65]
	global_load_dwordx4 v[70:73], v194, s[64:65] offset:16
	global_load_dwordx4 v[74:77], v194, s[66:67]
	global_load_dwordx4 v[78:81], v194, s[66:67] offset:16
	s_cmp_gt_i32 s56, 63
	s_cbranch_scc1 .Lup_samp
	s_mov_b32 exec_lo, 0xc000c000
	s_mov_b32 exec_hi, 0xc000c000
	ds_write_b128 v197, v[102:105]
	ds_write_b128 v197, v[98:101] offset:16
	ds_write_b128 v197, v[6:9] offset:2048
	ds_write_b128 v197, v[2:5] offset:2064
	s_mov_b64 exec, -1
	s_waitcnt lgkmcnt(0)
	s_barrier
	s_waitcnt vmcnt(0)
	s_cmp_eq_u32 s58, 0
	s_cbranch_scc1 .Lup_p00_zero
	v_add_u32_e32 v223, 0xfffffc00, v197
	ds_read_b128 v[162:165], v223
	ds_read_b128 v[166:169], v223 offset:16
	s_waitcnt lgkmcnt(0)
	s_branch .Lup_p00_go
.Lup_p00_zero:
	s_lshl_b32 s59, s56, 17
	s_add_u32 s72, s76, 0x33300000
	s_addc_u32 s73, s77, 0
	s_add_u32 s72, s72, s59
	s_addc_u32 s73, s73, 0
	s_add_u32 s74, s72, 0x8000
	s_addc_u32 s75, s73, 0
	v_and_b32_e32 v223, 15, v1
	v_lshl_add_u32 v223, v223, 16, v194
	s_mov_b32 exec_lo, 0x30003
	s_mov_b32 exec_hi, 0x30003
	global_store_dwordx4 v223, v[150:153], s[72:73]
	global_store_dwordx4 v223, v[146:149], s[72:73] offset:16
	global_store_dwordx4 v223, v[158:161], s[74:75]
	global_store_dwordx4 v223, v[154:157], s[74:75] offset:16
	s_mov_b64 exec, -1
	v_mov_b32_e32 v162, 0
	v_mov_b32_e32 v163, 0
	v_mov_b32_e32 v164, 0
	v_mov_b32_e32 v165, 0
	v_mov_b32_e32 v166, 0
	v_mov_b32_e32 v167, 0
	v_mov_b32_e32 v168, 0
	v_mov_b32_e32 v169, 0
	s_nop 1
.Lup_p00_go:
	v_fma_f32 v214, v66, v150, v74
	v_fma_f32 v215, v67, v151, v75
	v_fmac_f32_dpp v214, v150, v50 row_shr:1 row_mask:0xf bank_mask:0xf
	v_fmac_f32_dpp v215, v151, v51 row_shr:1 row_mask:0xf bank_mask:0xf
	v_fmac_f32_dpp v214, v162, v50 row_shl:15 row_mask:0xf bank_mask:0xf
	v_fmac_f32_dpp v215, v163, v51 row_shl:15 row_mask:0xf bank_mask:0xf
	v_fmac_f32_dpp v214, v150, v42 row_shr:2 row_mask:0xf bank_mask:0xf
	v_fmac_f32_dpp v215, v151, v43 row_shr:2 row_mask:0xf bank_mask:0xf
	v_fmac_f32_dpp v214, v162, v42 row_shl:14 row_mask:0xf bank_mask:0xf
	v_fmac_f32_dpp v215, v163, v43 row_shl:14 row_mask:0xf bank_mask:0xf
	v_mul_f32_e32 v216, 0x3d372713, v214
	v_mul_f32_e32 v217, 0x3d372713, v215
	v_mul_f32_e32 v218, 0x3fcc422a, v214
	v_mul_f32_e32 v219, 0x3fcc422a, v215
	v_fma_f32 v216, v214, v216, 1.0
	v_fma_f32 v217, v215, v217, 1.0
	v_mul_f32_e64 v218, v218, -v216
	v_mul_f32_e64 v219, v219, -v217
	v_mul_f32_e32 v218, 0x3fb8aa3b, v218
	v_mul_f32_e32 v219, 0x3fb8aa3b, v219
	v_exp_f32_e32 v218, v218
	v_exp_f32_e32 v219, v219
	v_add_f32_e32 v218, 1.0, v218
	v_add_f32_e32 v219, 1.0, v219
	v_rcp_f32_e32 v218, v218
	v_rcp_f32_e32 v219, v219
	v_mul_f32_e32 v216, v214, v218
	v_mul_f32_e32 v217, v215, v219
	v_mul_f32_e32 v158, v158, v216
	v_mul_f32_e32 v159, v159, v217
	v_fma_f32 v214, v68, v152, v76
	v_fma_f32 v215, v69, v153, v77
	v_fmac_f32_dpp v214, v152, v52 row_shr:1 row_mask:0xf bank_mask:0xf
	v_fmac_f32_dpp v215, v153, v53 row_shr:1 row_mask:0xf bank_mask:0xf
	v_fmac_f32_dpp v214, v164, v52 row_shl:15 row_mask:0xf bank_mask:0xf
	v_fmac_f32_dpp v215, v165, v53 row_shl:15 row_mask:0xf bank_mask:0xf
	v_fmac_f32_dpp v214, v152, v44 row_shr:2 row_mask:0xf bank_mask:0xf
	v_fmac_f32_dpp v215, v153, v45 row_shr:2 row_mask:0xf bank_mask:0xf
	v_fmac_f32_dpp v214, v164, v44 row_shl:14 row_mask:0xf bank_mask:0xf
	v_fmac_f32_dpp v215, v165, v45 row_shl:14 row_mask:0xf bank_mask:0xf
	v_mul_f32_e32 v216, 0x3d372713, v214
	v_mul_f32_e32 v217, 0x3d372713, v215
	v_mul_f32_e32 v218, 0x3fcc422a, v214
	v_mul_f32_e32 v219, 0x3fcc422a, v215
	v_fma_f32 v216, v214, v216, 1.0
	v_fma_f32 v217, v215, v217, 1.0
	v_mul_f32_e64 v218, v218, -v216
	v_mul_f32_e64 v219, v219, -v217
	v_mul_f32_e32 v218, 0x3fb8aa3b, v218
	v_mul_f32_e32 v219, 0x3fb8aa3b, v219
	v_exp_f32_e32 v218, v218
	v_exp_f32_e32 v219, v219
	v_add_f32_e32 v218, 1.0, v218
	v_add_f32_e32 v219, 1.0, v219
	v_rcp_f32_e32 v218, v218
	v_rcp_f32_e32 v219, v219
	v_mul_f32_e32 v216, v214, v218
	v_mul_f32_e32 v217, v215, v219
	v_mul_f32_e32 v160, v160, v216
	v_mul_f32_e32 v161, v161, v217
	v_fma_f32 v214, v70, v146, v78
	v_fma_f32 v215, v71, v147, v79
	v_fmac_f32_dpp v214, v146, v54 row_shr:1 row_mask:0xf bank_mask:0xf
	v_fmac_f32_dpp v215, v147, v55 row_shr:1 row_mask:0xf bank_mask:0xf
	v_fmac_f32_dpp v214, v166, v54 row_shl:15 row_mask:0xf bank_mask:0xf
; __device__ __forceinline__ u32x4 pack8(const f32x4 a, const f32x4 b) { u32x4 w; w.x = cvt_pk_bf16(a[0], a[1]); w.y = cvt_pk_bf16(a[2], a[3]); w.z = cvt_pk_bf16(b[0], b[1]); w.w = cvt_pk_bf16(b[2], b[3]); return w; }
; template <int CTRL> __device__ __forceinline__ float dppf(float v) { return __builtin_bit_cast(float, __builtin_amdgcn_update_dpp(0, __builtin_bit_cast(int, v), CTRL, 0xf, 0xf, true)); }
;     __device__ __forceinline__ void operator()(const f32x4 (&acc)[2][2][4][2], const Unit& u, int wr, int wc, int fr, int fq) const {
;     ...
;                 f32x4 hv[2];
; #pragma unroll
;                 for (int n = 0; n < 2; ++n) {
;                     const f32x4 a = acc[ai][0][m][n], b = acc[ai][1][m][n];
; #pragma unroll
;                     for (int i = 0; i < 4; ++i) {
;                         const float s1 = dppf<0x111>(a[i]), s2 = dppf<0x112>(a[i]);
;                         const float p1 = fr >= 1 ? s1 : w1[n][i], p2 = fr >= 2 ? s2 : w2[n][i];
;                         const float ac = cw0[n][i] * p2 + cw1[n][i] * p1 + cw2[n][i] * a[i] + cb[n][i];
;                         hv[n][i] = gelu_tanh(ac) * b[i];
;                     }
;                 }
;                 *(u32x4*)(hh + (size_t)row * DFF + cgc) = pack8(hv[0], hv[1]);
	v_fmac_f32_dpp v215, v167, v55 row_shl:15 row_mask:0xf bank_mask:0xf
	v_fmac_f32_dpp v214, v146, v46 row_shr:2 row_mask:0xf bank_mask:0xf
	v_fmac_f32_dpp v215, v147, v47 row_shr:2 row_mask:0xf bank_mask:0xf
	v_fmac_f32_dpp v214, v166, v46 row_shl:14 row_mask:0xf bank_mask:0xf
	v_fmac_f32_dpp v215, v167, v47 row_shl:14 row_mask:0xf bank_mask:0xf
	v_mul_f32_e32 v216, 0x3d372713, v214
	v_mul_f32_e32 v217, 0x3d372713, v215
	v_mul_f32_e32 v218, 0x3fcc422a, v214
	v_mul_f32_e32 v219, 0x3fcc422a, v215
	v_fma_f32 v216, v214, v216, 1.0
	v_fma_f32 v217, v215, v217, 1.0
	v_mul_f32_e64 v218, v218, -v216
	v_mul_f32_e64 v219, v219, -v217
	v_mul_f32_e32 v218, 0x3fb8aa3b, v218
	v_mul_f32_e32 v219, 0x3fb8aa3b, v219
	v_exp_f32_e32 v218, v218
	v_exp_f32_e32 v219, v219
	v_add_f32_e32 v218, 1.0, v218
	v_add_f32_e32 v219, 1.0, v219
	v_rcp_f32_e32 v218, v218
	v_rcp_f32_e32 v219, v219
	v_mul_f32_e32 v216, v214, v218
	v_mul_f32_e32 v217, v215, v219
	v_mul_f32_e32 v154, v154, v216
	v_mul_f32_e32 v155, v155, v217
	v_fma_f32 v214, v72, v148, v80
	v_fma_f32 v215, v73, v149, v81
	v_fmac_f32_dpp v214, v148, v56 row_shr:1 row_mask:0xf bank_mask:0xf
	v_fmac_f32_dpp v215, v149, v57 row_shr:1 row_mask:0xf bank_mask:0xf
	v_fmac_f32_dpp v214, v168, v56 row_shl:15 row_mask:0xf bank_mask:0xf
	v_fmac_f32_dpp v215, v169, v57 row_shl:15 row_mask:0xf bank_mask:0xf
	v_fmac_f32_dpp v214, v148, v48 row_shr:2 row_mask:0xf bank_mask:0xf
	v_fmac_f32_dpp v215, v149, v49 row_shr:2 row_mask:0xf bank_mask:0xf
	v_fmac_f32_dpp v214, v168, v48 row_shl:14 row_mask:0xf bank_mask:0xf
	v_fmac_f32_dpp v215, v169, v49 row_shl:14 row_mask:0xf bank_mask:0xf
	v_mul_f32_e32 v216, 0x3d372713, v214
	v_mul_f32_e32 v217, 0x3d372713, v215
	v_mul_f32_e32 v218, 0x3fcc422a, v214
	v_mul_f32_e32 v219, 0x3fcc422a, v215
	v_fma_f32 v216, v214, v216, 1.0
	v_fma_f32 v217, v215, v217, 1.0
	v_mul_f32_e64 v218, v218, -v216
	v_mul_f32_e64 v219, v219, -v217
	v_mul_f32_e32 v218, 0x3fb8aa3b, v218
	v_mul_f32_e32 v219, 0x3fb8aa3b, v219
	v_exp_f32_e32 v218, v218
	v_exp_f32_e32 v219, v219
	v_add_f32_e32 v218, 1.0, v218
	v_add_f32_e32 v219, 1.0, v219
	v_rcp_f32_e32 v218, v218
	v_rcp_f32_e32 v219, v219
	v_mul_f32_e32 v216, v214, v218
	v_mul_f32_e32 v217, v215, v219
	v_mul_f32_e32 v156, v156, v216
	v_mul_f32_e32 v157, v157, v217
	v_cvt_pk_bf16_f32 v158, v158, v159
	v_cvt_pk_bf16_f32 v159, v160, v161
	v_cvt_pk_bf16_f32 v160, v154, v155
	v_cvt_pk_bf16_f32 v161, v156, v157
	v_mov_b32_e32 v222, v195
	global_store_dwordx4 v222, v[158:161], s[70:71]
	v_fma_f32 v214, v66, v134, v74
	v_fma_f32 v215, v67, v135, v75
	v_fmac_f32_dpp v214, v134, v50 row_shr:1 row_mask:0xf bank_mask:0xf
	v_fmac_f32_dpp v215, v135, v51 row_shr:1 row_mask:0xf bank_mask:0xf
	v_fmac_f32_dpp v214, v150, v50 row_shl:15 row_mask:0xf bank_mask:0xf
	v_fmac_f32_dpp v215, v151, v51 row_shl:15 row_mask:0xf bank_mask:0xf
	v_fmac_f32_dpp v214, v134, v42 row_shr:2 row_mask:0xf bank_mask:0xf
	v_fmac_f32_dpp v215, v135, v43 row_shr:2 row_mask:0xf bank_mask:0xf
	v_fmac_f32_dpp v214, v150, v42 row_shl:14 row_mask:0xf bank_mask:0xf
	v_fmac_f32_dpp v215, v151, v43 row_shl:14 row_mask:0xf bank_mask:0xf
	v_mul_f32_e32 v216, 0x3d372713, v214
	v_mul_f32_e32 v217, 0x3d372713, v215
	v_mul_f32_e32 v218, 0x3fcc422a, v214
	v_mul_f32_e32 v219, 0x3fcc422a, v215
	v_fma_f32 v216, v214, v216, 1.0
	v_fma_f32 v217, v215, v217, 1.0
	v_mul_f32_e64 v218, v218, -v216
	v_mul_f32_e64 v219, v219, -v217
	v_mul_f32_e32 v218, 0x3fb8aa3b, v218
	v_mul_f32_e32 v219, 0x3fb8aa3b, v219
	v_exp_f32_e32 v218, v218
	v_exp_f32_e32 v219, v219
	v_add_f32_e32 v218, 1.0, v218
	v_add_f32_e32 v219, 1.0, v219
	v_rcp_f32_e32 v218, v218
	v_rcp_f32_e32 v219, v219
	v_mul_f32_e32 v216, v214, v218
	v_mul_f32_e32 v217, v215, v219
	v_mul_f32_e32 v142, v142, v216
	v_mul_f32_e32 v143, v143, v217
	v_fma_f32 v214, v68, v136, v76
	v_fma_f32 v215, v69, v137, v77
	v_fmac_f32_dpp v214, v136, v52 row_shr:1 row_mask:0xf bank_mask:0xf
	v_fmac_f32_dpp v215, v137, v53 row_shr:1 row_mask:0xf bank_mask:0xf
	v_fmac_f32_dpp v214, v152, v52 row_shl:15 row_mask:0xf bank_mask:0xf
	v_fmac_f32_dpp v215, v153, v53 row_shl:15 row_mask:0xf bank_mask:0xf
	v_fmac_f32_dpp v214, v136, v44 row_shr:2 row_mask:0xf bank_mask:0xf
	v_fmac_f32_dpp v215, v137, v45 row_shr:2 row_mask:0xf bank_mask:0xf
	v_fmac_f32_dpp v214, v152, v44 row_shl:14 row_mask:0xf bank_mask:0xf
	v_fmac_f32_dpp v215, v153, v45 row_shl:14 row_mask:0xf bank_mask:0xf
	v_mul_f32_e32 v216, 0x3d372713, v214
	v_mul_f32_e32 v217, 0x3d372713, v215
	v_mul_f32_e32 v218, 0x3fcc422a, v214
	v_mul_f32_e32 v219, 0x3fcc422a, v215
	v_fma_f32 v216, v214, v216, 1.0
	v_fma_f32 v217, v215, v217, 1.0
	v_mul_f32_e64 v218, v218, -v216
	v_mul_f32_e64 v219, v219, -v217
	v_mul_f32_e32 v218, 0x3fb8aa3b, v218
	v_mul_f32_e32 v219, 0x3fb8aa3b, v219
	v_exp_f32_e32 v218, v218
	v_exp_f32_e32 v219, v219
	v_add_f32_e32 v218, 1.0, v218
	v_add_f32_e32 v219, 1.0, v219
	v_rcp_f32_e32 v218, v218
	v_rcp_f32_e32 v219, v219
	v_mul_f32_e32 v216, v214, v218
	v_mul_f32_e32 v217, v215, v219
	v_mul_f32_e32 v144, v144, v216
	v_mul_f32_e32 v145, v145, v217
	v_fma_f32 v214, v70, v130, v78
	v_fma_f32 v215, v71, v131, v79
	v_fmac_f32_dpp v214, v130, v54 row_shr:1 row_mask:0xf bank_mask:0xf
	v_fmac_f32_dpp v215, v131, v55 row_shr:1 row_mask:0xf bank_mask:0xf
	v_fmac_f32_dpp v214, v146, v54 row_shl:15 row_mask:0xf bank_mask:0xf
	v_fmac_f32_dpp v215, v147, v55 row_shl:15 row_mask:0xf bank_mask:0xf
	v_fmac_f32_dpp v214, v130, v46 row_shr:2 row_mask:0xf bank_mask:0xf
	v_fmac_f32_dpp v215, v131, v47 row_shr:2 row_mask:0xf bank_mask:0xf
	v_fmac_f32_dpp v214, v146, v46 row_shl:14 row_mask:0xf bank_mask:0xf
	v_fmac_f32_dpp v215, v147, v47 row_shl:14 row_mask:0xf bank_mask:0xf
; __device__ __forceinline__ u32x4 pack8(const f32x4 a, const f32x4 b) { u32x4 w; w.x = cvt_pk_bf16(a[0], a[1]); w.y = cvt_pk_bf16(a[2], a[3]); w.z = cvt_pk_bf16(b[0], b[1]); w.w = cvt_pk_bf16(b[2], b[3]); return w; }
; template <int CTRL> __device__ __forceinline__ float dppf(float v) { return __builtin_bit_cast(float, __builtin_amdgcn_update_dpp(0, __builtin_bit_cast(int, v), CTRL, 0xf, 0xf, true)); }
;     __device__ __forceinline__ void operator()(const f32x4 (&acc)[2][2][4][2], const Unit& u, int wr, int wc, int fr, int fq) const {
;     ...
;                 f32x4 hv[2];
; #pragma unroll
;                 for (int n = 0; n < 2; ++n) {
;                     const f32x4 a = acc[ai][0][m][n], b = acc[ai][1][m][n];
; #pragma unroll
;                     for (int i = 0; i < 4; ++i) {
;                         const float s1 = dppf<0x111>(a[i]), s2 = dppf<0x112>(a[i]);
;                         const float p1 = fr >= 1 ? s1 : w1[n][i], p2 = fr >= 2 ? s2 : w2[n][i];
;                         const float ac = cw0[n][i] * p2 + cw1[n][i] * p1 + cw2[n][i] * a[i] + cb[n][i];
;                         hv[n][i] = gelu_tanh(ac) * b[i];
;                     }
;                 }
;                 *(u32x4*)(hh + (size_t)row * DFF + cgc) = pack8(hv[0], hv[1]);
	v_mul_f32_e32 v216, 0x3d372713, v214
	v_mul_f32_e32 v217, 0x3d372713, v215
	v_mul_f32_e32 v218, 0x3fcc422a, v214
	v_mul_f32_e32 v219, 0x3fcc422a, v215
	v_fma_f32 v216, v214, v216, 1.0
	v_fma_f32 v217, v215, v217, 1.0
	v_mul_f32_e64 v218, v218, -v216
	v_mul_f32_e64 v219, v219, -v217
	v_mul_f32_e32 v218, 0x3fb8aa3b, v218
	v_mul_f32_e32 v219, 0x3fb8aa3b, v219
	v_exp_f32_e32 v218, v218
	v_exp_f32_e32 v219, v219
	v_add_f32_e32 v218, 1.0, v218
	v_add_f32_e32 v219, 1.0, v219
	v_rcp_f32_e32 v218, v218
	v_rcp_f32_e32 v219, v219
	v_mul_f32_e32 v216, v214, v218
	v_mul_f32_e32 v217, v215, v219
	v_mul_f32_e32 v138, v138, v216
	v_mul_f32_e32 v139, v139, v217
	v_fma_f32 v214, v72, v132, v80
	v_fma_f32 v215, v73, v133, v81
	v_fmac_f32_dpp v214, v132, v56 row_shr:1 row_mask:0xf bank_mask:0xf
	v_fmac_f32_dpp v215, v133, v57 row_shr:1 row_mask:0xf bank_mask:0xf
	v_fmac_f32_dpp v214, v148, v56 row_shl:15 row_mask:0xf bank_mask:0xf
	v_fmac_f32_dpp v215, v149, v57 row_shl:15 row_mask:0xf bank_mask:0xf
	v_fmac_f32_dpp v214, v132, v48 row_shr:2 row_mask:0xf bank_mask:0xf
	v_fmac_f32_dpp v215, v133, v49 row_shr:2 row_mask:0xf bank_mask:0xf
	v_fmac_f32_dpp v214, v148, v48 row_shl:14 row_mask:0xf bank_mask:0xf
	v_fmac_f32_dpp v215, v149, v49 row_shl:14 row_mask:0xf bank_mask:0xf
	v_mul_f32_e32 v216, 0x3d372713, v214
	v_mul_f32_e32 v217, 0x3d372713, v215
	v_mul_f32_e32 v218, 0x3fcc422a, v214
	v_mul_f32_e32 v219, 0x3fcc422a, v215
	v_fma_f32 v216, v214, v216, 1.0
	v_fma_f32 v217, v215, v217, 1.0
	v_mul_f32_e64 v218, v218, -v216
	v_mul_f32_e64 v219, v219, -v217
	v_mul_f32_e32 v218, 0x3fb8aa3b, v218
	v_mul_f32_e32 v219, 0x3fb8aa3b, v219
	v_exp_f32_e32 v218, v218
	v_exp_f32_e32 v219, v219
	v_add_f32_e32 v218, 1.0, v218
	v_add_f32_e32 v219, 1.0, v219
	v_rcp_f32_e32 v218, v218
	v_rcp_f32_e32 v219, v219
	v_mul_f32_e32 v216, v214, v218
	v_mul_f32_e32 v217, v215, v219
	v_mul_f32_e32 v140, v140, v216
	v_mul_f32_e32 v141, v141, v217
	v_cvt_pk_bf16_f32 v142, v142, v143
	v_cvt_pk_bf16_f32 v143, v144, v145
	v_cvt_pk_bf16_f32 v144, v138, v139
	v_cvt_pk_bf16_f32 v145, v140, v141
	v_add_u32_e32 v222, 0x40000, v195
	global_store_dwordx4 v222, v[142:145], s[70:71]
	v_fma_f32 v214, v66, v118, v74
	v_fma_f32 v215, v67, v119, v75
	v_fmac_f32_dpp v214, v118, v50 row_shr:1 row_mask:0xf bank_mask:0xf
	v_fmac_f32_dpp v215, v119, v51 row_shr:1 row_mask:0xf bank_mask:0xf
	v_fmac_f32_dpp v214, v134, v50 row_shl:15 row_mask:0xf bank_mask:0xf
	v_fmac_f32_dpp v215, v135, v51 row_shl:15 row_mask:0xf bank_mask:0xf
	v_fmac_f32_dpp v214, v118, v42 row_shr:2 row_mask:0xf bank_mask:0xf
	v_fmac_f32_dpp v215, v119, v43 row_shr:2 row_mask:0xf bank_mask:0xf
	v_fmac_f32_dpp v214, v134, v42 row_shl:14 row_mask:0xf bank_mask:0xf
	v_fmac_f32_dpp v215, v135, v43 row_shl:14 row_mask:0xf bank_mask:0xf
	v_mul_f32_e32 v216, 0x3d372713, v214
	v_mul_f32_e32 v217, 0x3d372713, v215
	v_mul_f32_e32 v218, 0x3fcc422a, v214
	v_mul_f32_e32 v219, 0x3fcc422a, v215
	v_fma_f32 v216, v214, v216, 1.0
	v_fma_f32 v217, v215, v217, 1.0
	v_mul_f32_e64 v218, v218, -v216
	v_mul_f32_e64 v219, v219, -v217
	v_mul_f32_e32 v218, 0x3fb8aa3b, v218
	v_mul_f32_e32 v219, 0x3fb8aa3b, v219
	v_exp_f32_e32 v218, v218
	v_exp_f32_e32 v219, v219
	v_add_f32_e32 v218, 1.0, v218
	v_add_f32_e32 v219, 1.0, v219
	v_rcp_f32_e32 v218, v218
	v_rcp_f32_e32 v219, v219
	v_mul_f32_e32 v216, v214, v218
	v_mul_f32_e32 v217, v215, v219
	v_mul_f32_e32 v126, v126, v216
	v_mul_f32_e32 v127, v127, v217
	v_fma_f32 v214, v68, v120, v76
	v_fma_f32 v215, v69, v121, v77
	v_fmac_f32_dpp v214, v120, v52 row_shr:1 row_mask:0xf bank_mask:0xf
	v_fmac_f32_dpp v215, v121, v53 row_shr:1 row_mask:0xf bank_mask:0xf
	v_fmac_f32_dpp v214, v136, v52 row_shl:15 row_mask:0xf bank_mask:0xf
	v_fmac_f32_dpp v215, v137, v53 row_shl:15 row_mask:0xf bank_mask:0xf
	v_fmac_f32_dpp v214, v120, v44 row_shr:2 row_mask:0xf bank_mask:0xf
	v_fmac_f32_dpp v215, v121, v45 row_shr:2 row_mask:0xf bank_mask:0xf
	v_fmac_f32_dpp v214, v136, v44 row_shl:14 row_mask:0xf bank_mask:0xf
	v_fmac_f32_dpp v215, v137, v45 row_shl:14 row_mask:0xf bank_mask:0xf
	v_mul_f32_e32 v216, 0x3d372713, v214
	v_mul_f32_e32 v217, 0x3d372713, v215
	v_mul_f32_e32 v218, 0x3fcc422a, v214
	v_mul_f32_e32 v219, 0x3fcc422a, v215
	v_fma_f32 v216, v214, v216, 1.0
	v_fma_f32 v217, v215, v217, 1.0
	v_mul_f32_e64 v218, v218, -v216
	v_mul_f32_e64 v219, v219, -v217
	v_mul_f32_e32 v218, 0x3fb8aa3b, v218
	v_mul_f32_e32 v219, 0x3fb8aa3b, v219
	v_exp_f32_e32 v218, v218
	v_exp_f32_e32 v219, v219
	v_add_f32_e32 v218, 1.0, v218
	v_add_f32_e32 v219, 1.0, v219
	v_rcp_f32_e32 v218, v218
	v_rcp_f32_e32 v219, v219
	v_mul_f32_e32 v216, v214, v218
	v_mul_f32_e32 v217, v215, v219
	v_mul_f32_e32 v128, v128, v216
	v_mul_f32_e32 v129, v129, v217
	v_fma_f32 v214, v70, v114, v78
	v_fma_f32 v215, v71, v115, v79
	v_fmac_f32_dpp v214, v114, v54 row_shr:1 row_mask:0xf bank_mask:0xf
	v_fmac_f32_dpp v215, v115, v55 row_shr:1 row_mask:0xf bank_mask:0xf
	v_fmac_f32_dpp v214, v130, v54 row_shl:15 row_mask:0xf bank_mask:0xf
	v_fmac_f32_dpp v215, v131, v55 row_shl:15 row_mask:0xf bank_mask:0xf
	v_fmac_f32_dpp v214, v114, v46 row_shr:2 row_mask:0xf bank_mask:0xf
	v_fmac_f32_dpp v215, v115, v47 row_shr:2 row_mask:0xf bank_mask:0xf
	v_fmac_f32_dpp v214, v130, v46 row_shl:14 row_mask:0xf bank_mask:0xf
	v_fmac_f32_dpp v215, v131, v47 row_shl:14 row_mask:0xf bank_mask:0xf
	v_mul_f32_e32 v216, 0x3d372713, v214
	v_mul_f32_e32 v217, 0x3d372713, v215
	v_mul_f32_e32 v218, 0x3fcc422a, v214
	v_mul_f32_e32 v219, 0x3fcc422a, v215
	v_fma_f32 v216, v214, v216, 1.0
	v_fma_f32 v217, v215, v217, 1.0
	v_mul_f32_e64 v218, v218, -v216
	v_mul_f32_e64 v219, v219, -v217
	v_mul_f32_e32 v218, 0x3fb8aa3b, v218
; __device__ __forceinline__ u32x4 pack8(const f32x4 a, const f32x4 b) { u32x4 w; w.x = cvt_pk_bf16(a[0], a[1]); w.y = cvt_pk_bf16(a[2], a[3]); w.z = cvt_pk_bf16(b[0], b[1]); w.w = cvt_pk_bf16(b[2], b[3]); return w; }
; template <int CTRL> __device__ __forceinline__ float dppf(float v) { return __builtin_bit_cast(float, __builtin_amdgcn_update_dpp(0, __builtin_bit_cast(int, v), CTRL, 0xf, 0xf, true)); }
;     __device__ __forceinline__ void operator()(const f32x4 (&acc)[2][2][4][2], const Unit& u, int wr, int wc, int fr, int fq) const {
;     ...
;                 f32x4 hv[2];
; #pragma unroll
;                 for (int n = 0; n < 2; ++n) {
;                     const f32x4 a = acc[ai][0][m][n], b = acc[ai][1][m][n];
; #pragma unroll
;                     for (int i = 0; i < 4; ++i) {
;                         const float s1 = dppf<0x111>(a[i]), s2 = dppf<0x112>(a[i]);
;                         const float p1 = fr >= 1 ? s1 : w1[n][i], p2 = fr >= 2 ? s2 : w2[n][i];
;                         const float ac = cw0[n][i] * p2 + cw1[n][i] * p1 + cw2[n][i] * a[i] + cb[n][i];
;                         hv[n][i] = gelu_tanh(ac) * b[i];
;                     }
;                 }
;                 *(u32x4*)(hh + (size_t)row * DFF + cgc) = pack8(hv[0], hv[1]);
	v_mul_f32_e32 v219, 0x3fb8aa3b, v219
	v_exp_f32_e32 v218, v218
	v_exp_f32_e32 v219, v219
	v_add_f32_e32 v218, 1.0, v218
	v_add_f32_e32 v219, 1.0, v219
	v_rcp_f32_e32 v218, v218
	v_rcp_f32_e32 v219, v219
	v_mul_f32_e32 v216, v214, v218
	v_mul_f32_e32 v217, v215, v219
	v_mul_f32_e32 v122, v122, v216
	v_mul_f32_e32 v123, v123, v217
	v_fma_f32 v214, v72, v116, v80
	v_fma_f32 v215, v73, v117, v81
	v_fmac_f32_dpp v214, v116, v56 row_shr:1 row_mask:0xf bank_mask:0xf
	v_fmac_f32_dpp v215, v117, v57 row_shr:1 row_mask:0xf bank_mask:0xf
	v_fmac_f32_dpp v214, v132, v56 row_shl:15 row_mask:0xf bank_mask:0xf
	v_fmac_f32_dpp v215, v133, v57 row_shl:15 row_mask:0xf bank_mask:0xf
	v_fmac_f32_dpp v214, v116, v48 row_shr:2 row_mask:0xf bank_mask:0xf
	v_fmac_f32_dpp v215, v117, v49 row_shr:2 row_mask:0xf bank_mask:0xf
	v_fmac_f32_dpp v214, v132, v48 row_shl:14 row_mask:0xf bank_mask:0xf
	v_fmac_f32_dpp v215, v133, v49 row_shl:14 row_mask:0xf bank_mask:0xf
	v_mul_f32_e32 v216, 0x3d372713, v214
	v_mul_f32_e32 v217, 0x3d372713, v215
	v_mul_f32_e32 v218, 0x3fcc422a, v214
	v_mul_f32_e32 v219, 0x3fcc422a, v215
	v_fma_f32 v216, v214, v216, 1.0
	v_fma_f32 v217, v215, v217, 1.0
	v_mul_f32_e64 v218, v218, -v216
	v_mul_f32_e64 v219, v219, -v217
	v_mul_f32_e32 v218, 0x3fb8aa3b, v218
	v_mul_f32_e32 v219, 0x3fb8aa3b, v219
	v_exp_f32_e32 v218, v218
	v_exp_f32_e32 v219, v219
	v_add_f32_e32 v218, 1.0, v218
	v_add_f32_e32 v219, 1.0, v219
	v_rcp_f32_e32 v218, v218
	v_rcp_f32_e32 v219, v219
	v_mul_f32_e32 v216, v214, v218
	v_mul_f32_e32 v217, v215, v219
	v_mul_f32_e32 v124, v124, v216
	v_mul_f32_e32 v125, v125, v217
	v_cvt_pk_bf16_f32 v126, v126, v127
	v_cvt_pk_bf16_f32 v127, v128, v129
	v_cvt_pk_bf16_f32 v128, v122, v123
	v_cvt_pk_bf16_f32 v129, v124, v125
	v_add_u32_e32 v222, 0x80000, v195
	global_store_dwordx4 v222, v[126:129], s[70:71]
	v_fma_f32 v214, v66, v102, v74
	v_fma_f32 v215, v67, v103, v75
	v_fmac_f32_dpp v214, v102, v50 row_shr:1 row_mask:0xf bank_mask:0xf
	v_fmac_f32_dpp v215, v103, v51 row_shr:1 row_mask:0xf bank_mask:0xf
	v_fmac_f32_dpp v214, v118, v50 row_shl:15 row_mask:0xf bank_mask:0xf
	v_fmac_f32_dpp v215, v119, v51 row_shl:15 row_mask:0xf bank_mask:0xf
	v_fmac_f32_dpp v214, v102, v42 row_shr:2 row_mask:0xf bank_mask:0xf
	v_fmac_f32_dpp v215, v103, v43 row_shr:2 row_mask:0xf bank_mask:0xf
	v_fmac_f32_dpp v214, v118, v42 row_shl:14 row_mask:0xf bank_mask:0xf
	v_fmac_f32_dpp v215, v119, v43 row_shl:14 row_mask:0xf bank_mask:0xf
	v_mul_f32_e32 v216, 0x3d372713, v214
	v_mul_f32_e32 v217, 0x3d372713, v215
	v_mul_f32_e32 v218, 0x3fcc422a, v214
	v_mul_f32_e32 v219, 0x3fcc422a, v215
	v_fma_f32 v216, v214, v216, 1.0
	v_fma_f32 v217, v215, v217, 1.0
	v_mul_f32_e64 v218, v218, -v216
	v_mul_f32_e64 v219, v219, -v217
	v_mul_f32_e32 v218, 0x3fb8aa3b, v218
	v_mul_f32_e32 v219, 0x3fb8aa3b, v219
	v_exp_f32_e32 v218, v218
	v_exp_f32_e32 v219, v219
	v_add_f32_e32 v218, 1.0, v218
	v_add_f32_e32 v219, 1.0, v219
	v_rcp_f32_e32 v218, v218
	v_rcp_f32_e32 v219, v219
	v_mul_f32_e32 v216, v214, v218
	v_mul_f32_e32 v217, v215, v219
	v_mul_f32_e32 v110, v110, v216
	v_mul_f32_e32 v111, v111, v217
	v_fma_f32 v214, v68, v104, v76
	v_fma_f32 v215, v69, v105, v77
	v_fmac_f32_dpp v214, v104, v52 row_shr:1 row_mask:0xf bank_mask:0xf
	v_fmac_f32_dpp v215, v105, v53 row_shr:1 row_mask:0xf bank_mask:0xf
	v_fmac_f32_dpp v214, v120, v52 row_shl:15 row_mask:0xf bank_mask:0xf
	v_fmac_f32_dpp v215, v121, v53 row_shl:15 row_mask:0xf bank_mask:0xf
	v_fmac_f32_dpp v214, v104, v44 row_shr:2 row_mask:0xf bank_mask:0xf
	v_fmac_f32_dpp v215, v105, v45 row_shr:2 row_mask:0xf bank_mask:0xf
	v_fmac_f32_dpp v214, v120, v44 row_shl:14 row_mask:0xf bank_mask:0xf
	v_fmac_f32_dpp v215, v121, v45 row_shl:14 row_mask:0xf bank_mask:0xf
	v_mul_f32_e32 v216, 0x3d372713, v214
	v_mul_f32_e32 v217, 0x3d372713, v215
	v_mul_f32_e32 v218, 0x3fcc422a, v214
	v_mul_f32_e32 v219, 0x3fcc422a, v215
	v_fma_f32 v216, v214, v216, 1.0
	v_fma_f32 v217, v215, v217, 1.0
	v_mul_f32_e64 v218, v218, -v216
	v_mul_f32_e64 v219, v219, -v217
	v_mul_f32_e32 v218, 0x3fb8aa3b, v218
	v_mul_f32_e32 v219, 0x3fb8aa3b, v219
	v_exp_f32_e32 v218, v218
	v_exp_f32_e32 v219, v219
	v_add_f32_e32 v218, 1.0, v218
	v_add_f32_e32 v219, 1.0, v219
	v_rcp_f32_e32 v218, v218
	v_rcp_f32_e32 v219, v219
	v_mul_f32_e32 v216, v214, v218
	v_mul_f32_e32 v217, v215, v219
	v_mul_f32_e32 v112, v112, v216
	v_mul_f32_e32 v113, v113, v217
	v_fma_f32 v214, v70, v98, v78
	v_fma_f32 v215, v71, v99, v79
	v_fmac_f32_dpp v214, v98, v54 row_shr:1 row_mask:0xf bank_mask:0xf
	v_fmac_f32_dpp v215, v99, v55 row_shr:1 row_mask:0xf bank_mask:0xf
	v_fmac_f32_dpp v214, v114, v54 row_shl:15 row_mask:0xf bank_mask:0xf
	v_fmac_f32_dpp v215, v115, v55 row_shl:15 row_mask:0xf bank_mask:0xf
	v_fmac_f32_dpp v214, v98, v46 row_shr:2 row_mask:0xf bank_mask:0xf
	v_fmac_f32_dpp v215, v99, v47 row_shr:2 row_mask:0xf bank_mask:0xf
	v_fmac_f32_dpp v214, v114, v46 row_shl:14 row_mask:0xf bank_mask:0xf
	v_fmac_f32_dpp v215, v115, v47 row_shl:14 row_mask:0xf bank_mask:0xf
	v_mul_f32_e32 v216, 0x3d372713, v214
	v_mul_f32_e32 v217, 0x3d372713, v215
	v_mul_f32_e32 v218, 0x3fcc422a, v214
	v_mul_f32_e32 v219, 0x3fcc422a, v215
	v_fma_f32 v216, v214, v216, 1.0
	v_fma_f32 v217, v215, v217, 1.0
	v_mul_f32_e64 v218, v218, -v216
	v_mul_f32_e64 v219, v219, -v217
	v_mul_f32_e32 v218, 0x3fb8aa3b, v218
	v_mul_f32_e32 v219, 0x3fb8aa3b, v219
	v_exp_f32_e32 v218, v218
	v_exp_f32_e32 v219, v219
	v_add_f32_e32 v218, 1.0, v218
	v_add_f32_e32 v219, 1.0, v219
	v_rcp_f32_e32 v218, v218
	v_rcp_f32_e32 v219, v219
	v_mul_f32_e32 v216, v214, v218
	v_mul_f32_e32 v217, v215, v219
	v_mul_f32_e32 v106, v106, v216
	v_mul_f32_e32 v107, v107, v217
; __device__ __forceinline__ u32x4 pack8(const f32x4 a, const f32x4 b) { u32x4 w; w.x = cvt_pk_bf16(a[0], a[1]); w.y = cvt_pk_bf16(a[2], a[3]); w.z = cvt_pk_bf16(b[0], b[1]); w.w = cvt_pk_bf16(b[2], b[3]); return w; }
; template <int CTRL> __device__ __forceinline__ float dppf(float v) { return __builtin_bit_cast(float, __builtin_amdgcn_update_dpp(0, __builtin_bit_cast(int, v), CTRL, 0xf, 0xf, true)); }
; #define PG8_LAS __attribute__((address_space(3)))
;     __device__ __forceinline__ void operator()(const f32x4 (&acc)[2][2][4][2], const Unit& u, int wr, int wc, int fr, int fq) const {
;     ...
;                 } else if (m == 0) {
;                     if (blk > 0) {
; #pragma unroll
;                         for (int n = 0; n < 2; ++n) { const f32x4 c14 = *(const PG8_LAS f32x4*)(xbuf + ((blk - 1) * 2 + 0) * 128 + cl + 4 * n), c15 = *(const PG8_LAS f32x4*)(xbuf + ((blk - 1) * 2 + 1) * 128 + cl + 4 * n);
;                             w1[n] = c15; w2[n] = fr == 0 ? c14 : c15; }
;                     } else { w1[0] = w1[1] = w2[0] = w2[1] = (f32x4){0.f, 0.f, 0.f, 0.f}; }
;                 } else {
; #pragma unroll
;                     for (int n = 0; n < 2; ++n)
; #pragma unroll
;                         for (int i = 0; i < 4; ++i) { const float ap = acc[ai][0][m - 1][n][i]; w1[n][i] = dppf<0x10F>(ap); w2[n][i] = dppf<0x10E>(ap); }
;                 }
;                 f32x4 hv[2];
; #pragma unroll
;                 for (int n = 0; n < 2; ++n) {
;                     const f32x4 a = acc[ai][0][m][n], b = acc[ai][1][m][n];
; #pragma unroll
;                     for (int i = 0; i < 4; ++i) {
;                         const float s1 = dppf<0x111>(a[i]), s2 = dppf<0x112>(a[i]);
;                         const float p1 = fr >= 1 ? s1 : w1[n][i], p2 = fr >= 2 ? s2 : w2[n][i];
;                         const float ac = cw0[n][i] * p2 + cw1[n][i] * p1 + cw2[n][i] * a[i] + cb[n][i];
;                         hv[n][i] = gelu_tanh(ac) * b[i];
;                     }
;                 }
;                 *(u32x4*)(hh + (size_t)row * DFF + cgc) = pack8(hv[0], hv[1]);
	v_fma_f32 v214, v72, v100, v80
	v_fma_f32 v215, v73, v101, v81
	v_fmac_f32_dpp v214, v100, v56 row_shr:1 row_mask:0xf bank_mask:0xf
	v_fmac_f32_dpp v215, v101, v57 row_shr:1 row_mask:0xf bank_mask:0xf
	v_fmac_f32_dpp v214, v116, v56 row_shl:15 row_mask:0xf bank_mask:0xf
	v_fmac_f32_dpp v215, v117, v57 row_shl:15 row_mask:0xf bank_mask:0xf
	v_fmac_f32_dpp v214, v100, v48 row_shr:2 row_mask:0xf bank_mask:0xf
	v_fmac_f32_dpp v215, v101, v49 row_shr:2 row_mask:0xf bank_mask:0xf
	v_fmac_f32_dpp v214, v116, v48 row_shl:14 row_mask:0xf bank_mask:0xf
	v_fmac_f32_dpp v215, v117, v49 row_shl:14 row_mask:0xf bank_mask:0xf
	v_mul_f32_e32 v216, 0x3d372713, v214
	v_mul_f32_e32 v217, 0x3d372713, v215
	v_mul_f32_e32 v218, 0x3fcc422a, v214
	v_mul_f32_e32 v219, 0x3fcc422a, v215
	v_fma_f32 v216, v214, v216, 1.0
	v_fma_f32 v217, v215, v217, 1.0
	v_mul_f32_e64 v218, v218, -v216
	v_mul_f32_e64 v219, v219, -v217
	v_mul_f32_e32 v218, 0x3fb8aa3b, v218
	v_mul_f32_e32 v219, 0x3fb8aa3b, v219
	v_exp_f32_e32 v218, v218
	v_exp_f32_e32 v219, v219
	v_add_f32_e32 v218, 1.0, v218
	v_add_f32_e32 v219, 1.0, v219
	v_rcp_f32_e32 v218, v218
	v_rcp_f32_e32 v219, v219
	v_mul_f32_e32 v216, v214, v218
	v_mul_f32_e32 v217, v215, v219
	v_mul_f32_e32 v108, v108, v216
	v_mul_f32_e32 v109, v109, v217
	v_cvt_pk_bf16_f32 v110, v110, v111
	v_cvt_pk_bf16_f32 v111, v112, v113
	v_cvt_pk_bf16_f32 v112, v106, v107
	v_cvt_pk_bf16_f32 v113, v108, v109
	v_add_u32_e32 v222, 0xc0000, v195
	global_store_dwordx4 v222, v[110:113], s[70:71]
	ds_read_b128 v[162:165], v197 offset:1024
	ds_read_b128 v[166:169], v197 offset:1040
	s_waitcnt lgkmcnt(0)
	v_fma_f32 v214, v66, v86, v74
	v_fma_f32 v215, v67, v87, v75
	v_fmac_f32_dpp v214, v86, v50 row_shr:1 row_mask:0xf bank_mask:0xf
	v_fmac_f32_dpp v215, v87, v51 row_shr:1 row_mask:0xf bank_mask:0xf
	v_fmac_f32_dpp v214, v162, v50 row_shl:15 row_mask:0xf bank_mask:0xf
	v_fmac_f32_dpp v215, v163, v51 row_shl:15 row_mask:0xf bank_mask:0xf
	v_fmac_f32_dpp v214, v86, v42 row_shr:2 row_mask:0xf bank_mask:0xf
	v_fmac_f32_dpp v215, v87, v43 row_shr:2 row_mask:0xf bank_mask:0xf
	v_fmac_f32_dpp v214, v162, v42 row_shl:14 row_mask:0xf bank_mask:0xf
	v_fmac_f32_dpp v215, v163, v43 row_shl:14 row_mask:0xf bank_mask:0xf
	v_mul_f32_e32 v216, 0x3d372713, v214
	v_mul_f32_e32 v217, 0x3d372713, v215
	v_mul_f32_e32 v218, 0x3fcc422a, v214
	v_mul_f32_e32 v219, 0x3fcc422a, v215
	v_fma_f32 v216, v214, v216, 1.0
	v_fma_f32 v217, v215, v217, 1.0
	v_mul_f32_e64 v218, v218, -v216
	v_mul_f32_e64 v219, v219, -v217
	v_mul_f32_e32 v218, 0x3fb8aa3b, v218
	v_mul_f32_e32 v219, 0x3fb8aa3b, v219
	v_exp_f32_e32 v218, v218
	v_exp_f32_e32 v219, v219
	v_add_f32_e32 v218, 1.0, v218
	v_add_f32_e32 v219, 1.0, v219
	v_rcp_f32_e32 v218, v218
	v_rcp_f32_e32 v219, v219
	v_mul_f32_e32 v216, v214, v218
	v_mul_f32_e32 v217, v215, v219
	v_mul_f32_e32 v94, v94, v216
	v_mul_f32_e32 v95, v95, v217
	v_fma_f32 v214, v68, v88, v76
	v_fma_f32 v215, v69, v89, v77
	v_fmac_f32_dpp v214, v88, v52 row_shr:1 row_mask:0xf bank_mask:0xf
	v_fmac_f32_dpp v215, v89, v53 row_shr:1 row_mask:0xf bank_mask:0xf
	v_fmac_f32_dpp v214, v164, v52 row_shl:15 row_mask:0xf bank_mask:0xf
	v_fmac_f32_dpp v215, v165, v53 row_shl:15 row_mask:0xf bank_mask:0xf
	v_fmac_f32_dpp v214, v88, v44 row_shr:2 row_mask:0xf bank_mask:0xf
	v_fmac_f32_dpp v215, v89, v45 row_shr:2 row_mask:0xf bank_mask:0xf
	v_fmac_f32_dpp v214, v164, v44 row_shl:14 row_mask:0xf bank_mask:0xf
	v_fmac_f32_dpp v215, v165, v45 row_shl:14 row_mask:0xf bank_mask:0xf
	v_mul_f32_e32 v216, 0x3d372713, v214
	v_mul_f32_e32 v217, 0x3d372713, v215
	v_mul_f32_e32 v218, 0x3fcc422a, v214
	v_mul_f32_e32 v219, 0x3fcc422a, v215
	v_fma_f32 v216, v214, v216, 1.0
	v_fma_f32 v217, v215, v217, 1.0
	v_mul_f32_e64 v218, v218, -v216
	v_mul_f32_e64 v219, v219, -v217
	v_mul_f32_e32 v218, 0x3fb8aa3b, v218
	v_mul_f32_e32 v219, 0x3fb8aa3b, v219
	v_exp_f32_e32 v218, v218
	v_exp_f32_e32 v219, v219
	v_add_f32_e32 v218, 1.0, v218
	v_add_f32_e32 v219, 1.0, v219
	v_rcp_f32_e32 v218, v218
	v_rcp_f32_e32 v219, v219
	v_mul_f32_e32 v216, v214, v218
	v_mul_f32_e32 v217, v215, v219
	v_mul_f32_e32 v96, v96, v216
	v_mul_f32_e32 v97, v97, v217
	v_fma_f32 v214, v70, v82, v78
	v_fma_f32 v215, v71, v83, v79
	v_fmac_f32_dpp v214, v82, v54 row_shr:1 row_mask:0xf bank_mask:0xf
	v_fmac_f32_dpp v215, v83, v55 row_shr:1 row_mask:0xf bank_mask:0xf
	v_fmac_f32_dpp v214, v166, v54 row_shl:15 row_mask:0xf bank_mask:0xf
	v_fmac_f32_dpp v215, v167, v55 row_shl:15 row_mask:0xf bank_mask:0xf
	v_fmac_f32_dpp v214, v82, v46 row_shr:2 row_mask:0xf bank_mask:0xf
	v_fmac_f32_dpp v215, v83, v47 row_shr:2 row_mask:0xf bank_mask:0xf
	v_fmac_f32_dpp v214, v166, v46 row_shl:14 row_mask:0xf bank_mask:0xf
	v_fmac_f32_dpp v215, v167, v47 row_shl:14 row_mask:0xf bank_mask:0xf
	v_mul_f32_e32 v216, 0x3d372713, v214
	v_mul_f32_e32 v217, 0x3d372713, v215
	v_mul_f32_e32 v218, 0x3fcc422a, v214
	v_mul_f32_e32 v219, 0x3fcc422a, v215
	v_fma_f32 v216, v214, v216, 1.0
	v_fma_f32 v217, v215, v217, 1.0
	v_mul_f32_e64 v218, v218, -v216
	v_mul_f32_e64 v219, v219, -v217
	v_mul_f32_e32 v218, 0x3fb8aa3b, v218
	v_mul_f32_e32 v219, 0x3fb8aa3b, v219
	v_exp_f32_e32 v218, v218
	v_exp_f32_e32 v219, v219
	v_add_f32_e32 v218, 1.0, v218
	v_add_f32_e32 v219, 1.0, v219
	v_rcp_f32_e32 v218, v218
	v_rcp_f32_e32 v219, v219
	v_mul_f32_e32 v216, v214, v218
	v_mul_f32_e32 v217, v215, v219
	v_mul_f32_e32 v90, v90, v216
	v_mul_f32_e32 v91, v91, v217
	v_fma_f32 v214, v72, v84, v80
	v_fma_f32 v215, v73, v85, v81
	v_fmac_f32_dpp v214, v84, v56 row_shr:1 row_mask:0xf bank_mask:0xf
	v_fmac_f32_dpp v215, v85, v57 row_shr:1 row_mask:0xf bank_mask:0xf
	v_fmac_f32_dpp v214, v168, v56 row_shl:15 row_mask:0xf bank_mask:0xf
; __device__ __forceinline__ u32x4 pack8(const f32x4 a, const f32x4 b) { u32x4 w; w.x = cvt_pk_bf16(a[0], a[1]); w.y = cvt_pk_bf16(a[2], a[3]); w.z = cvt_pk_bf16(b[0], b[1]); w.w = cvt_pk_bf16(b[2], b[3]); return w; }
; template <int CTRL> __device__ __forceinline__ float dppf(float v) { return __builtin_bit_cast(float, __builtin_amdgcn_update_dpp(0, __builtin_bit_cast(int, v), CTRL, 0xf, 0xf, true)); }
;     __device__ __forceinline__ void operator()(const f32x4 (&acc)[2][2][4][2], const Unit& u, int wr, int wc, int fr, int fq) const {
;     ...
;                 f32x4 hv[2];
; #pragma unroll
;                 for (int n = 0; n < 2; ++n) {
;                     const f32x4 a = acc[ai][0][m][n], b = acc[ai][1][m][n];
; #pragma unroll
;                     for (int i = 0; i < 4; ++i) {
;                         const float s1 = dppf<0x111>(a[i]), s2 = dppf<0x112>(a[i]);
;                         const float p1 = fr >= 1 ? s1 : w1[n][i], p2 = fr >= 2 ? s2 : w2[n][i];
;                         const float ac = cw0[n][i] * p2 + cw1[n][i] * p1 + cw2[n][i] * a[i] + cb[n][i];
;                         hv[n][i] = gelu_tanh(ac) * b[i];
;                     }
;                 }
;                 *(u32x4*)(hh + (size_t)row * DFF + cgc) = pack8(hv[0], hv[1]);
	v_fmac_f32_dpp v215, v169, v57 row_shl:15 row_mask:0xf bank_mask:0xf
	v_fmac_f32_dpp v214, v84, v48 row_shr:2 row_mask:0xf bank_mask:0xf
	v_fmac_f32_dpp v215, v85, v49 row_shr:2 row_mask:0xf bank_mask:0xf
	v_fmac_f32_dpp v214, v168, v48 row_shl:14 row_mask:0xf bank_mask:0xf
	v_fmac_f32_dpp v215, v169, v49 row_shl:14 row_mask:0xf bank_mask:0xf
	v_mul_f32_e32 v216, 0x3d372713, v214
	v_mul_f32_e32 v217, 0x3d372713, v215
	v_mul_f32_e32 v218, 0x3fcc422a, v214
	v_mul_f32_e32 v219, 0x3fcc422a, v215
	v_fma_f32 v216, v214, v216, 1.0
	v_fma_f32 v217, v215, v217, 1.0
	v_mul_f32_e64 v218, v218, -v216
	v_mul_f32_e64 v219, v219, -v217
	v_mul_f32_e32 v218, 0x3fb8aa3b, v218
	v_mul_f32_e32 v219, 0x3fb8aa3b, v219
	v_exp_f32_e32 v218, v218
	v_exp_f32_e32 v219, v219
	v_add_f32_e32 v218, 1.0, v218
	v_add_f32_e32 v219, 1.0, v219
	v_rcp_f32_e32 v218, v218
	v_rcp_f32_e32 v219, v219
	v_mul_f32_e32 v216, v214, v218
	v_mul_f32_e32 v217, v215, v219
	v_mul_f32_e32 v92, v92, v216
	v_mul_f32_e32 v93, v93, v217
	v_cvt_pk_bf16_f32 v94, v94, v95
	v_cvt_pk_bf16_f32 v95, v96, v97
	v_cvt_pk_bf16_f32 v96, v90, v91
	v_cvt_pk_bf16_f32 v97, v92, v93
	v_add_u32_e32 v222, 0x200000, v195
	global_store_dwordx4 v222, v[94:97], s[70:71]
	v_fma_f32 v214, v66, v38, v74
	v_fma_f32 v215, v67, v39, v75
	v_fmac_f32_dpp v214, v38, v50 row_shr:1 row_mask:0xf bank_mask:0xf
	v_fmac_f32_dpp v215, v39, v51 row_shr:1 row_mask:0xf bank_mask:0xf
	v_fmac_f32_dpp v214, v86, v50 row_shl:15 row_mask:0xf bank_mask:0xf
	v_fmac_f32_dpp v215, v87, v51 row_shl:15 row_mask:0xf bank_mask:0xf
	v_fmac_f32_dpp v214, v38, v42 row_shr:2 row_mask:0xf bank_mask:0xf
	v_fmac_f32_dpp v215, v39, v43 row_shr:2 row_mask:0xf bank_mask:0xf
	v_fmac_f32_dpp v214, v86, v42 row_shl:14 row_mask:0xf bank_mask:0xf
	v_fmac_f32_dpp v215, v87, v43 row_shl:14 row_mask:0xf bank_mask:0xf
	v_mul_f32_e32 v216, 0x3d372713, v214
	v_mul_f32_e32 v217, 0x3d372713, v215
	v_mul_f32_e32 v218, 0x3fcc422a, v214
	v_mul_f32_e32 v219, 0x3fcc422a, v215
	v_fma_f32 v216, v214, v216, 1.0
	v_fma_f32 v217, v215, v217, 1.0
	v_mul_f32_e64 v218, v218, -v216
	v_mul_f32_e64 v219, v219, -v217
	v_mul_f32_e32 v218, 0x3fb8aa3b, v218
	v_mul_f32_e32 v219, 0x3fb8aa3b, v219
	v_exp_f32_e32 v218, v218
	v_exp_f32_e32 v219, v219
	v_add_f32_e32 v218, 1.0, v218
	v_add_f32_e32 v219, 1.0, v219
	v_rcp_f32_e32 v218, v218
	v_rcp_f32_e32 v219, v219
	v_mul_f32_e32 v216, v214, v218
	v_mul_f32_e32 v217, v215, v219
	v_mul_f32_e32 v62, v62, v216
	v_mul_f32_e32 v63, v63, v217
	v_fma_f32 v214, v68, v40, v76
	v_fma_f32 v215, v69, v41, v77
	v_fmac_f32_dpp v214, v40, v52 row_shr:1 row_mask:0xf bank_mask:0xf
	v_fmac_f32_dpp v215, v41, v53 row_shr:1 row_mask:0xf bank_mask:0xf
	v_fmac_f32_dpp v214, v88, v52 row_shl:15 row_mask:0xf bank_mask:0xf
	v_fmac_f32_dpp v215, v89, v53 row_shl:15 row_mask:0xf bank_mask:0xf
	v_fmac_f32_dpp v214, v40, v44 row_shr:2 row_mask:0xf bank_mask:0xf
	v_fmac_f32_dpp v215, v41, v45 row_shr:2 row_mask:0xf bank_mask:0xf
	v_fmac_f32_dpp v214, v88, v44 row_shl:14 row_mask:0xf bank_mask:0xf
	v_fmac_f32_dpp v215, v89, v45 row_shl:14 row_mask:0xf bank_mask:0xf
	v_mul_f32_e32 v216, 0x3d372713, v214
	v_mul_f32_e32 v217, 0x3d372713, v215
	v_mul_f32_e32 v218, 0x3fcc422a, v214
	v_mul_f32_e32 v219, 0x3fcc422a, v215
	v_fma_f32 v216, v214, v216, 1.0
	v_fma_f32 v217, v215, v217, 1.0
	v_mul_f32_e64 v218, v218, -v216
	v_mul_f32_e64 v219, v219, -v217
	v_mul_f32_e32 v218, 0x3fb8aa3b, v218
	v_mul_f32_e32 v219, 0x3fb8aa3b, v219
	v_exp_f32_e32 v218, v218
	v_exp_f32_e32 v219, v219
	v_add_f32_e32 v218, 1.0, v218
	v_add_f32_e32 v219, 1.0, v219
	v_rcp_f32_e32 v218, v218
	v_rcp_f32_e32 v219, v219
	v_mul_f32_e32 v216, v214, v218
	v_mul_f32_e32 v217, v215, v219
	v_mul_f32_e32 v64, v64, v216
	v_mul_f32_e32 v65, v65, v217
	v_fma_f32 v214, v70, v34, v78
	v_fma_f32 v215, v71, v35, v79
	v_fmac_f32_dpp v214, v34, v54 row_shr:1 row_mask:0xf bank_mask:0xf
	v_fmac_f32_dpp v215, v35, v55 row_shr:1 row_mask:0xf bank_mask:0xf
	v_fmac_f32_dpp v214, v82, v54 row_shl:15 row_mask:0xf bank_mask:0xf
	v_fmac_f32_dpp v215, v83, v55 row_shl:15 row_mask:0xf bank_mask:0xf
	v_fmac_f32_dpp v214, v34, v46 row_shr:2 row_mask:0xf bank_mask:0xf
	v_fmac_f32_dpp v215, v35, v47 row_shr:2 row_mask:0xf bank_mask:0xf
	v_fmac_f32_dpp v214, v82, v46 row_shl:14 row_mask:0xf bank_mask:0xf
	v_fmac_f32_dpp v215, v83, v47 row_shl:14 row_mask:0xf bank_mask:0xf
	v_mul_f32_e32 v216, 0x3d372713, v214
	v_mul_f32_e32 v217, 0x3d372713, v215
	v_mul_f32_e32 v218, 0x3fcc422a, v214
	v_mul_f32_e32 v219, 0x3fcc422a, v215
	v_fma_f32 v216, v214, v216, 1.0
	v_fma_f32 v217, v215, v217, 1.0
	v_mul_f32_e64 v218, v218, -v216
	v_mul_f32_e64 v219, v219, -v217
	v_mul_f32_e32 v218, 0x3fb8aa3b, v218
	v_mul_f32_e32 v219, 0x3fb8aa3b, v219
	v_exp_f32_e32 v218, v218
	v_exp_f32_e32 v219, v219
	v_add_f32_e32 v218, 1.0, v218
	v_add_f32_e32 v219, 1.0, v219
	v_rcp_f32_e32 v218, v218
	v_rcp_f32_e32 v219, v219
	v_mul_f32_e32 v216, v214, v218
	v_mul_f32_e32 v217, v215, v219
	v_mul_f32_e32 v58, v58, v216
	v_mul_f32_e32 v59, v59, v217
	v_fma_f32 v214, v72, v36, v80
	v_fma_f32 v215, v73, v37, v81
	v_fmac_f32_dpp v214, v36, v56 row_shr:1 row_mask:0xf bank_mask:0xf
	v_fmac_f32_dpp v215, v37, v57 row_shr:1 row_mask:0xf bank_mask:0xf
	v_fmac_f32_dpp v214, v84, v56 row_shl:15 row_mask:0xf bank_mask:0xf
	v_fmac_f32_dpp v215, v85, v57 row_shl:15 row_mask:0xf bank_mask:0xf
	v_fmac_f32_dpp v214, v36, v48 row_shr:2 row_mask:0xf bank_mask:0xf
	v_fmac_f32_dpp v215, v37, v49 row_shr:2 row_mask:0xf bank_mask:0xf
	v_fmac_f32_dpp v214, v84, v48 row_shl:14 row_mask:0xf bank_mask:0xf
	v_fmac_f32_dpp v215, v85, v49 row_shl:14 row_mask:0xf bank_mask:0xf
	v_mul_f32_e32 v216, 0x3d372713, v214
; __device__ __forceinline__ u32x4 pack8(const f32x4 a, const f32x4 b) { u32x4 w; w.x = cvt_pk_bf16(a[0], a[1]); w.y = cvt_pk_bf16(a[2], a[3]); w.z = cvt_pk_bf16(b[0], b[1]); w.w = cvt_pk_bf16(b[2], b[3]); return w; }
; template <int CTRL> __device__ __forceinline__ float dppf(float v) { return __builtin_bit_cast(float, __builtin_amdgcn_update_dpp(0, __builtin_bit_cast(int, v), CTRL, 0xf, 0xf, true)); }
;     __device__ __forceinline__ void operator()(const f32x4 (&acc)[2][2][4][2], const Unit& u, int wr, int wc, int fr, int fq) const {
;     ...
;                 f32x4 hv[2];
; #pragma unroll
;                 for (int n = 0; n < 2; ++n) {
;                     const f32x4 a = acc[ai][0][m][n], b = acc[ai][1][m][n];
; #pragma unroll
;                     for (int i = 0; i < 4; ++i) {
;                         const float s1 = dppf<0x111>(a[i]), s2 = dppf<0x112>(a[i]);
;                         const float p1 = fr >= 1 ? s1 : w1[n][i], p2 = fr >= 2 ? s2 : w2[n][i];
;                         const float ac = cw0[n][i] * p2 + cw1[n][i] * p1 + cw2[n][i] * a[i] + cb[n][i];
;                         hv[n][i] = gelu_tanh(ac) * b[i];
;                     }
;                 }
;                 *(u32x4*)(hh + (size_t)row * DFF + cgc) = pack8(hv[0], hv[1]);
	v_mul_f32_e32 v217, 0x3d372713, v215
	v_mul_f32_e32 v218, 0x3fcc422a, v214
	v_mul_f32_e32 v219, 0x3fcc422a, v215
	v_fma_f32 v216, v214, v216, 1.0
	v_fma_f32 v217, v215, v217, 1.0
	v_mul_f32_e64 v218, v218, -v216
	v_mul_f32_e64 v219, v219, -v217
	v_mul_f32_e32 v218, 0x3fb8aa3b, v218
	v_mul_f32_e32 v219, 0x3fb8aa3b, v219
	v_exp_f32_e32 v218, v218
	v_exp_f32_e32 v219, v219
	v_add_f32_e32 v218, 1.0, v218
	v_add_f32_e32 v219, 1.0, v219
	v_rcp_f32_e32 v218, v218
	v_rcp_f32_e32 v219, v219
	v_mul_f32_e32 v216, v214, v218
	v_mul_f32_e32 v217, v215, v219
	v_mul_f32_e32 v60, v60, v216
	v_mul_f32_e32 v61, v61, v217
	v_cvt_pk_bf16_f32 v62, v62, v63
	v_cvt_pk_bf16_f32 v63, v64, v65
	v_cvt_pk_bf16_f32 v64, v58, v59
	v_cvt_pk_bf16_f32 v65, v60, v61
	v_add_u32_e32 v222, 0x240000, v195
	global_store_dwordx4 v222, v[62:65], s[70:71]
	v_fma_f32 v214, v66, v22, v74
	v_fma_f32 v215, v67, v23, v75
	v_fmac_f32_dpp v214, v22, v50 row_shr:1 row_mask:0xf bank_mask:0xf
	v_fmac_f32_dpp v215, v23, v51 row_shr:1 row_mask:0xf bank_mask:0xf
	v_fmac_f32_dpp v214, v38, v50 row_shl:15 row_mask:0xf bank_mask:0xf
	v_fmac_f32_dpp v215, v39, v51 row_shl:15 row_mask:0xf bank_mask:0xf
	v_fmac_f32_dpp v214, v22, v42 row_shr:2 row_mask:0xf bank_mask:0xf
	v_fmac_f32_dpp v215, v23, v43 row_shr:2 row_mask:0xf bank_mask:0xf
	v_fmac_f32_dpp v214, v38, v42 row_shl:14 row_mask:0xf bank_mask:0xf
	v_fmac_f32_dpp v215, v39, v43 row_shl:14 row_mask:0xf bank_mask:0xf
	v_mul_f32_e32 v216, 0x3d372713, v214
	v_mul_f32_e32 v217, 0x3d372713, v215
	v_mul_f32_e32 v218, 0x3fcc422a, v214
	v_mul_f32_e32 v219, 0x3fcc422a, v215
	v_fma_f32 v216, v214, v216, 1.0
	v_fma_f32 v217, v215, v217, 1.0
	v_mul_f32_e64 v218, v218, -v216
	v_mul_f32_e64 v219, v219, -v217
	v_mul_f32_e32 v218, 0x3fb8aa3b, v218
	v_mul_f32_e32 v219, 0x3fb8aa3b, v219
	v_exp_f32_e32 v218, v218
	v_exp_f32_e32 v219, v219
	v_add_f32_e32 v218, 1.0, v218
	v_add_f32_e32 v219, 1.0, v219
	v_rcp_f32_e32 v218, v218
	v_rcp_f32_e32 v219, v219
	v_mul_f32_e32 v216, v214, v218
	v_mul_f32_e32 v217, v215, v219
	v_mul_f32_e32 v30, v30, v216
	v_mul_f32_e32 v31, v31, v217
	v_fma_f32 v214, v68, v24, v76
	v_fma_f32 v215, v69, v25, v77
	v_fmac_f32_dpp v214, v24, v52 row_shr:1 row_mask:0xf bank_mask:0xf
	v_fmac_f32_dpp v215, v25, v53 row_shr:1 row_mask:0xf bank_mask:0xf
	v_fmac_f32_dpp v214, v40, v52 row_shl:15 row_mask:0xf bank_mask:0xf
	v_fmac_f32_dpp v215, v41, v53 row_shl:15 row_mask:0xf bank_mask:0xf
	v_fmac_f32_dpp v214, v24, v44 row_shr:2 row_mask:0xf bank_mask:0xf
	v_fmac_f32_dpp v215, v25, v45 row_shr:2 row_mask:0xf bank_mask:0xf
	v_fmac_f32_dpp v214, v40, v44 row_shl:14 row_mask:0xf bank_mask:0xf
	v_fmac_f32_dpp v215, v41, v45 row_shl:14 row_mask:0xf bank_mask:0xf
	v_mul_f32_e32 v216, 0x3d372713, v214
	v_mul_f32_e32 v217, 0x3d372713, v215
	v_mul_f32_e32 v218, 0x3fcc422a, v214
	v_mul_f32_e32 v219, 0x3fcc422a, v215
	v_fma_f32 v216, v214, v216, 1.0
	v_fma_f32 v217, v215, v217, 1.0
	v_mul_f32_e64 v218, v218, -v216
	v_mul_f32_e64 v219, v219, -v217
	v_mul_f32_e32 v218, 0x3fb8aa3b, v218
	v_mul_f32_e32 v219, 0x3fb8aa3b, v219
	v_exp_f32_e32 v218, v218
	v_exp_f32_e32 v219, v219
	v_add_f32_e32 v218, 1.0, v218
	v_add_f32_e32 v219, 1.0, v219
	v_rcp_f32_e32 v218, v218
	v_rcp_f32_e32 v219, v219
	v_mul_f32_e32 v216, v214, v218
	v_mul_f32_e32 v217, v215, v219
	v_mul_f32_e32 v32, v32, v216
	v_mul_f32_e32 v33, v33, v217
	v_fma_f32 v214, v70, v18, v78
	v_fma_f32 v215, v71, v19, v79
	v_fmac_f32_dpp v214, v18, v54 row_shr:1 row_mask:0xf bank_mask:0xf
	v_fmac_f32_dpp v215, v19, v55 row_shr:1 row_mask:0xf bank_mask:0xf
	v_fmac_f32_dpp v214, v34, v54 row_shl:15 row_mask:0xf bank_mask:0xf
	v_fmac_f32_dpp v215, v35, v55 row_shl:15 row_mask:0xf bank_mask:0xf
	v_fmac_f32_dpp v214, v18, v46 row_shr:2 row_mask:0xf bank_mask:0xf
	v_fmac_f32_dpp v215, v19, v47 row_shr:2 row_mask:0xf bank_mask:0xf
	v_fmac_f32_dpp v214, v34, v46 row_shl:14 row_mask:0xf bank_mask:0xf
	v_fmac_f32_dpp v215, v35, v47 row_shl:14 row_mask:0xf bank_mask:0xf
	v_mul_f32_e32 v216, 0x3d372713, v214
	v_mul_f32_e32 v217, 0x3d372713, v215
	v_mul_f32_e32 v218, 0x3fcc422a, v214
	v_mul_f32_e32 v219, 0x3fcc422a, v215
	v_fma_f32 v216, v214, v216, 1.0
	v_fma_f32 v217, v215, v217, 1.0
	v_mul_f32_e64 v218, v218, -v216
	v_mul_f32_e64 v219, v219, -v217
	v_mul_f32_e32 v218, 0x3fb8aa3b, v218
	v_mul_f32_e32 v219, 0x3fb8aa3b, v219
	v_exp_f32_e32 v218, v218
	v_exp_f32_e32 v219, v219
	v_add_f32_e32 v218, 1.0, v218
	v_add_f32_e32 v219, 1.0, v219
	v_rcp_f32_e32 v218, v218
	v_rcp_f32_e32 v219, v219
	v_mul_f32_e32 v216, v214, v218
	v_mul_f32_e32 v217, v215, v219
	v_mul_f32_e32 v26, v26, v216
	v_mul_f32_e32 v27, v27, v217
	v_fma_f32 v214, v72, v20, v80
	v_fma_f32 v215, v73, v21, v81
	v_fmac_f32_dpp v214, v20, v56 row_shr:1 row_mask:0xf bank_mask:0xf
	v_fmac_f32_dpp v215, v21, v57 row_shr:1 row_mask:0xf bank_mask:0xf
	v_fmac_f32_dpp v214, v36, v56 row_shl:15 row_mask:0xf bank_mask:0xf
	v_fmac_f32_dpp v215, v37, v57 row_shl:15 row_mask:0xf bank_mask:0xf
	v_fmac_f32_dpp v214, v20, v48 row_shr:2 row_mask:0xf bank_mask:0xf
	v_fmac_f32_dpp v215, v21, v49 row_shr:2 row_mask:0xf bank_mask:0xf
	v_fmac_f32_dpp v214, v36, v48 row_shl:14 row_mask:0xf bank_mask:0xf
	v_fmac_f32_dpp v215, v37, v49 row_shl:14 row_mask:0xf bank_mask:0xf
	v_mul_f32_e32 v216, 0x3d372713, v214
	v_mul_f32_e32 v217, 0x3d372713, v215
	v_mul_f32_e32 v218, 0x3fcc422a, v214
	v_mul_f32_e32 v219, 0x3fcc422a, v215
	v_fma_f32 v216, v214, v216, 1.0
	v_fma_f32 v217, v215, v217, 1.0
	v_mul_f32_e64 v218, v218, -v216
	v_mul_f32_e64 v219, v219, -v217
	v_mul_f32_e32 v218, 0x3fb8aa3b, v218
	v_mul_f32_e32 v219, 0x3fb8aa3b, v219
	v_exp_f32_e32 v218, v218
	v_exp_f32_e32 v219, v219
; __device__ __forceinline__ u32x4 pack8(const f32x4 a, const f32x4 b) { u32x4 w; w.x = cvt_pk_bf16(a[0], a[1]); w.y = cvt_pk_bf16(a[2], a[3]); w.z = cvt_pk_bf16(b[0], b[1]); w.w = cvt_pk_bf16(b[2], b[3]); return w; }
; template <int CTRL> __device__ __forceinline__ float dppf(float v) { return __builtin_bit_cast(float, __builtin_amdgcn_update_dpp(0, __builtin_bit_cast(int, v), CTRL, 0xf, 0xf, true)); }
;     __device__ __forceinline__ void operator()(const f32x4 (&acc)[2][2][4][2], const Unit& u, int wr, int wc, int fr, int fq) const {
;     ...
;                 f32x4 hv[2];
; #pragma unroll
;                 for (int n = 0; n < 2; ++n) {
;                     const f32x4 a = acc[ai][0][m][n], b = acc[ai][1][m][n];
; #pragma unroll
;                     for (int i = 0; i < 4; ++i) {
;                         const float s1 = dppf<0x111>(a[i]), s2 = dppf<0x112>(a[i]);
;                         const float p1 = fr >= 1 ? s1 : w1[n][i], p2 = fr >= 2 ? s2 : w2[n][i];
;                         const float ac = cw0[n][i] * p2 + cw1[n][i] * p1 + cw2[n][i] * a[i] + cb[n][i];
;                         hv[n][i] = gelu_tanh(ac) * b[i];
;                     }
;                 }
;                 *(u32x4*)(hh + (size_t)row * DFF + cgc) = pack8(hv[0], hv[1]);
;                 if (samp) {
;                     if (fr >= 14) { const int bs = (row - MP) >> 4; float* p = out + O_CVS + ((size_t)bs * 2 + (fr - 14)) * DFF + cgc; *(f32x4*)p = acc[ai][0][m][0]; *(f32x4*)(p + 4) = acc[ai][0][m][1]; }
;                 } else {
;                     if (blk == 3 && m == 3 && fr >= 14) { float* p = tail + ((size_t)u.pm * 2 + (fr - 14)) * DFF + cgc; *(f32x4*)p = acc[ai][0][m][0]; *(f32x4*)(p + 4) = acc[ai][0][m][1];
;                         if ((u.pm & 31) == 31) { float* q = out + O_CVP + ((size_t)(u.pm >> 5) * 2 + (fr - 14)) * DFF + cgc; *(f32x4*)q = acc[ai][0][m][0]; *(f32x4*)(q + 4) = acc[ai][0][m][1]; } }
	v_add_f32_e32 v218, 1.0, v218
	v_add_f32_e32 v219, 1.0, v219
	v_rcp_f32_e32 v218, v218
	v_rcp_f32_e32 v219, v219
	v_mul_f32_e32 v216, v214, v218
	v_mul_f32_e32 v217, v215, v219
	v_mul_f32_e32 v28, v28, v216
	v_mul_f32_e32 v29, v29, v217
	v_cvt_pk_bf16_f32 v30, v30, v31
	v_cvt_pk_bf16_f32 v31, v32, v33
	v_cvt_pk_bf16_f32 v32, v26, v27
	v_cvt_pk_bf16_f32 v33, v28, v29
	v_add_u32_e32 v222, 0x280000, v195
	global_store_dwordx4 v222, v[30:33], s[70:71]
	v_fma_f32 v214, v66, v6, v74
	v_fma_f32 v215, v67, v7, v75
	v_fmac_f32_dpp v214, v6, v50 row_shr:1 row_mask:0xf bank_mask:0xf
	v_fmac_f32_dpp v215, v7, v51 row_shr:1 row_mask:0xf bank_mask:0xf
	v_fmac_f32_dpp v214, v22, v50 row_shl:15 row_mask:0xf bank_mask:0xf
	v_fmac_f32_dpp v215, v23, v51 row_shl:15 row_mask:0xf bank_mask:0xf
	v_fmac_f32_dpp v214, v6, v42 row_shr:2 row_mask:0xf bank_mask:0xf
	v_fmac_f32_dpp v215, v7, v43 row_shr:2 row_mask:0xf bank_mask:0xf
	v_fmac_f32_dpp v214, v22, v42 row_shl:14 row_mask:0xf bank_mask:0xf
	v_fmac_f32_dpp v215, v23, v43 row_shl:14 row_mask:0xf bank_mask:0xf
	v_mul_f32_e32 v216, 0x3d372713, v214
	v_mul_f32_e32 v217, 0x3d372713, v215
	v_mul_f32_e32 v218, 0x3fcc422a, v214
	v_mul_f32_e32 v219, 0x3fcc422a, v215
	v_fma_f32 v216, v214, v216, 1.0
	v_fma_f32 v217, v215, v217, 1.0
	v_mul_f32_e64 v218, v218, -v216
	v_mul_f32_e64 v219, v219, -v217
	v_mul_f32_e32 v218, 0x3fb8aa3b, v218
	v_mul_f32_e32 v219, 0x3fb8aa3b, v219
	v_exp_f32_e32 v218, v218
	v_exp_f32_e32 v219, v219
	v_add_f32_e32 v218, 1.0, v218
	v_add_f32_e32 v219, 1.0, v219
	v_rcp_f32_e32 v218, v218
	v_rcp_f32_e32 v219, v219
	v_mul_f32_e32 v216, v214, v218
	v_mul_f32_e32 v217, v215, v219
	v_mul_f32_e32 v14, v14, v216
	v_mul_f32_e32 v15, v15, v217
	v_fma_f32 v214, v68, v8, v76
	v_fma_f32 v215, v69, v9, v77
	v_fmac_f32_dpp v214, v8, v52 row_shr:1 row_mask:0xf bank_mask:0xf
	v_fmac_f32_dpp v215, v9, v53 row_shr:1 row_mask:0xf bank_mask:0xf
	v_fmac_f32_dpp v214, v24, v52 row_shl:15 row_mask:0xf bank_mask:0xf
	v_fmac_f32_dpp v215, v25, v53 row_shl:15 row_mask:0xf bank_mask:0xf
	v_fmac_f32_dpp v214, v8, v44 row_shr:2 row_mask:0xf bank_mask:0xf
	v_fmac_f32_dpp v215, v9, v45 row_shr:2 row_mask:0xf bank_mask:0xf
	v_fmac_f32_dpp v214, v24, v44 row_shl:14 row_mask:0xf bank_mask:0xf
	v_fmac_f32_dpp v215, v25, v45 row_shl:14 row_mask:0xf bank_mask:0xf
	v_mul_f32_e32 v216, 0x3d372713, v214
	v_mul_f32_e32 v217, 0x3d372713, v215
	v_mul_f32_e32 v218, 0x3fcc422a, v214
	v_mul_f32_e32 v219, 0x3fcc422a, v215
	v_fma_f32 v216, v214, v216, 1.0
	v_fma_f32 v217, v215, v217, 1.0
	v_mul_f32_e64 v218, v218, -v216
	v_mul_f32_e64 v219, v219, -v217
	v_mul_f32_e32 v218, 0x3fb8aa3b, v218
	v_mul_f32_e32 v219, 0x3fb8aa3b, v219
	v_exp_f32_e32 v218, v218
	v_exp_f32_e32 v219, v219
	v_add_f32_e32 v218, 1.0, v218
	v_add_f32_e32 v219, 1.0, v219
	v_rcp_f32_e32 v218, v218
	v_rcp_f32_e32 v219, v219
	v_mul_f32_e32 v216, v214, v218
	v_mul_f32_e32 v217, v215, v219
	v_mul_f32_e32 v16, v16, v216
	v_mul_f32_e32 v17, v17, v217
	v_fma_f32 v214, v70, v2, v78
	v_fma_f32 v215, v71, v3, v79
	v_fmac_f32_dpp v214, v2, v54 row_shr:1 row_mask:0xf bank_mask:0xf
	v_fmac_f32_dpp v215, v3, v55 row_shr:1 row_mask:0xf bank_mask:0xf
	v_fmac_f32_dpp v214, v18, v54 row_shl:15 row_mask:0xf bank_mask:0xf
	v_fmac_f32_dpp v215, v19, v55 row_shl:15 row_mask:0xf bank_mask:0xf
	v_fmac_f32_dpp v214, v2, v46 row_shr:2 row_mask:0xf bank_mask:0xf
	v_fmac_f32_dpp v215, v3, v47 row_shr:2 row_mask:0xf bank_mask:0xf
	v_fmac_f32_dpp v214, v18, v46 row_shl:14 row_mask:0xf bank_mask:0xf
	v_fmac_f32_dpp v215, v19, v47 row_shl:14 row_mask:0xf bank_mask:0xf
	v_mul_f32_e32 v216, 0x3d372713, v214
	v_mul_f32_e32 v217, 0x3d372713, v215
	v_mul_f32_e32 v218, 0x3fcc422a, v214
	v_mul_f32_e32 v219, 0x3fcc422a, v215
	v_fma_f32 v216, v214, v216, 1.0
	v_fma_f32 v217, v215, v217, 1.0
	v_mul_f32_e64 v218, v218, -v216
	v_mul_f32_e64 v219, v219, -v217
	v_mul_f32_e32 v218, 0x3fb8aa3b, v218
	v_mul_f32_e32 v219, 0x3fb8aa3b, v219
	v_exp_f32_e32 v218, v218
	v_exp_f32_e32 v219, v219
	v_add_f32_e32 v218, 1.0, v218
	v_add_f32_e32 v219, 1.0, v219
	v_rcp_f32_e32 v218, v218
	v_rcp_f32_e32 v219, v219
	v_mul_f32_e32 v216, v214, v218
	v_mul_f32_e32 v217, v215, v219
	v_mul_f32_e32 v10, v10, v216
	v_mul_f32_e32 v11, v11, v217
	v_fma_f32 v214, v72, v4, v80
	v_fma_f32 v215, v73, v5, v81
	v_fmac_f32_dpp v214, v4, v56 row_shr:1 row_mask:0xf bank_mask:0xf
	v_fmac_f32_dpp v215, v5, v57 row_shr:1 row_mask:0xf bank_mask:0xf
	v_fmac_f32_dpp v214, v20, v56 row_shl:15 row_mask:0xf bank_mask:0xf
	v_fmac_f32_dpp v215, v21, v57 row_shl:15 row_mask:0xf bank_mask:0xf
	v_fmac_f32_dpp v214, v4, v48 row_shr:2 row_mask:0xf bank_mask:0xf
	v_fmac_f32_dpp v215, v5, v49 row_shr:2 row_mask:0xf bank_mask:0xf
	v_fmac_f32_dpp v214, v20, v48 row_shl:14 row_mask:0xf bank_mask:0xf
	v_fmac_f32_dpp v215, v21, v49 row_shl:14 row_mask:0xf bank_mask:0xf
	v_mul_f32_e32 v216, 0x3d372713, v214
	v_mul_f32_e32 v217, 0x3d372713, v215
	v_mul_f32_e32 v218, 0x3fcc422a, v214
	v_mul_f32_e32 v219, 0x3fcc422a, v215
	v_fma_f32 v216, v214, v216, 1.0
	v_fma_f32 v217, v215, v217, 1.0
	v_mul_f32_e64 v218, v218, -v216
	v_mul_f32_e64 v219, v219, -v217
	v_mul_f32_e32 v218, 0x3fb8aa3b, v218
	v_mul_f32_e32 v219, 0x3fb8aa3b, v219
	v_exp_f32_e32 v218, v218
	v_exp_f32_e32 v219, v219
	v_add_f32_e32 v218, 1.0, v218
	v_add_f32_e32 v219, 1.0, v219
	v_rcp_f32_e32 v218, v218
	v_rcp_f32_e32 v219, v219
	v_mul_f32_e32 v216, v214, v218
	v_mul_f32_e32 v217, v215, v219
	v_mul_f32_e32 v12, v12, v216
	v_mul_f32_e32 v13, v13, v217
	v_cvt_pk_bf16_f32 v14, v14, v15
	v_cvt_pk_bf16_f32 v15, v16, v17
	v_cvt_pk_bf16_f32 v16, v10, v11
	v_cvt_pk_bf16_f32 v17, v12, v13
	v_add_u32_e32 v222, 0x2c0000, v195
	global_store_dwordx4 v222, v[14:17], s[70:71]
	s_cmp_eq_u32 s58, 1
	s_cbranch_scc0 .Lup_exit
	s_lshl_b32 s59, s56, 16
	s_add_u32 s72, s76, 0x32e00000
	s_addc_u32 s73, s77, 0
	s_add_u32 s72, s72, s59
	s_addc_u32 s73, s73, 0
	s_mov_b32 exec_lo, 0xc000c000
	s_mov_b32 exec_hi, 0xc000c000
	global_store_dwordx4 v196, v[6:9], s[72:73]
	global_store_dwordx4 v196, v[2:5], s[72:73] offset:16
	s_and_b32 s59, s56, 31
	s_cmp_eq_u32 s59, 31
	s_cbranch_scc0 .Lup_exit
	s_lshr_b32 s59, s56, 5
	s_lshl_b32 s59, s59, 16
	s_add_u32 s72, s78, 0x18480000
	s_addc_u32 s73, s79, 0
	s_add_u32 s72, s72, s59
	s_addc_u32 s73, s73, 0
	global_store_dwordx4 v196, v[6:9], s[72:73]
	global_store_dwordx4 v196, v[2:5], s[72:73] offset:16
	s_branch .Lup_exit
; #define PG8_LAS __attribute__((address_space(3)))
;     __device__ __forceinline__ void operator()(const f32x4 (&acc)[2][2][4][2], const Unit& u, int wr, int wc, int fr, int fq) const {
;     ...
;                 if (samp) {
;                     const int bs = (row - MP) >> 4;
; #pragma unroll
;                     for (int n = 0; n < 2; ++n) { const f32x4 s0 = *(const f32x4*)(state + ((size_t)bs * 2 + 0) * DFF + cgc + 4 * n), s1 = *(const f32x4*)(state + ((size_t)bs * 2 + 1) * DFF + cgc + 4 * n);
;                         w1[n] = s1; w2[n] = fr == 0 ? s0 : s1; }
;                 } else if (m == 0) {
;                     if (blk > 0) {
; #pragma unroll
;                         for (int n = 0; n < 2; ++n) { const f32x4 c14 = *(const PG8_LAS f32x4*)(xbuf + ((blk - 1) * 2 + 0) * 128 + cl + 4 * n), c15 = *(const PG8_LAS f32x4*)(xbuf + ((blk - 1) * 2 + 1) * 128 + cl + 4 * n);
;                             w1[n] = c15; w2[n] = fr == 0 ? c14 : c15; }
;                     } else { w1[0] = w1[1] = w2[0] = w2[1] = (f32x4){0.f, 0.f, 0.f, 0.f}; }
;                 } else {
; #pragma unroll
;                     for (int n = 0; n < 2; ++n)
; #pragma unroll
;                         for (int i = 0; i < 4; ++i) { const float ap = acc[ai][0][m - 1][n][i]; w1[n][i] = dppf<0x10F>(ap); w2[n][i] = dppf<0x10E>(ap); }
;                 }
;                 f32x4 hv[2];
; #pragma unroll
;                 for (int n = 0; n < 2; ++n) {
;                     const f32x4 a = acc[ai][0][m][n], b = acc[ai][1][m][n];
; #pragma unroll
;                     for (int i = 0; i < 4; ++i) {
;                         const float s1 = dppf<0x111>(a[i]), s2 = dppf<0x112>(a[i]);
;                         const float p1 = fr >= 1 ? s1 : w1[n][i], p2 = fr >= 2 ? s2 : w2[n][i];
;                         const float ac = cw0[n][i] * p2 + cw1[n][i] * p1 + cw2[n][i] * a[i] + cb[n][i];
;                         hv[n][i] = gelu_tanh(ac) * b[i];
;                     }
;                 }
;                 *(u32x4*)(hh + (size_t)row * DFF + cgc) = pack8(hv[0], hv[1]);
;                 if (samp) {
;                     if (fr >= 14) { const int bs = (row - MP) >> 4; float* p = out + O_CVS + ((size_t)bs * 2 + (fr - 14)) * DFF + cgc; *(f32x4*)p = acc[ai][0][m][0]; *(f32x4*)(p + 4) = acc[ai][0][m][1]; }
.Lup_samp:
	v_readlane_b32 s74, v251, 17
	v_readlane_b32 s75, v251, 18
	s_sub_u32 s59, s56, 64
	s_lshl_b32 s59, s59, 4
	s_lshl_b32 s31, s58, 2
	s_add_u32 s59, s59, s31
	s_lshl_b32 s59, s59, 16
	s_add_u32 s74, s74, s59
	s_addc_u32 s75, s75, 0
	s_add_u32 s72, s78, 0x18ca4000
	s_addc_u32 s73, s79, 0
	s_add_u32 s72, s72, s59
	s_addc_u32 s73, s73, 0
	s_waitcnt vmcnt(0)
	s_mov_b64 s[86:87], s[74:75]
	global_load_dwordx4 v[162:165], v196, s[86:87]
	global_load_dwordx4 v[166:169], v196, s[86:87] offset:16
	s_mov_b64 s[86:87], s[72:73]
	s_mov_b32 exec_lo, 0xc000c000
	s_mov_b32 exec_hi, 0xc000c000
	global_store_dwordx4 v196, v[150:153], s[86:87]
	global_store_dwordx4 v196, v[146:149], s[86:87] offset:16
	s_mov_b64 exec, -1
	s_waitcnt vmcnt(2)
	v_fma_f32 v214, v66, v150, v74
	v_fma_f32 v215, v67, v151, v75
	v_fmac_f32_dpp v214, v150, v50 row_shr:1 row_mask:0xf bank_mask:0xf
	v_fmac_f32_dpp v215, v151, v51 row_shr:1 row_mask:0xf bank_mask:0xf
	v_fmac_f32_dpp v214, v162, v50 row_shl:15 row_mask:0xf bank_mask:0xf
	v_fmac_f32_dpp v215, v163, v51 row_shl:15 row_mask:0xf bank_mask:0xf
	v_fmac_f32_dpp v214, v150, v42 row_shr:2 row_mask:0xf bank_mask:0xf
	v_fmac_f32_dpp v215, v151, v43 row_shr:2 row_mask:0xf bank_mask:0xf
	v_fmac_f32_dpp v214, v162, v42 row_shl:14 row_mask:0xf bank_mask:0xf
	v_fmac_f32_dpp v215, v163, v43 row_shl:14 row_mask:0xf bank_mask:0xf
	v_mul_f32_e32 v216, 0x3d372713, v214
	v_mul_f32_e32 v217, 0x3d372713, v215
	v_mul_f32_e32 v218, 0x3fcc422a, v214
	v_mul_f32_e32 v219, 0x3fcc422a, v215
	v_fma_f32 v216, v214, v216, 1.0
	v_fma_f32 v217, v215, v217, 1.0
	v_mul_f32_e64 v218, v218, -v216
	v_mul_f32_e64 v219, v219, -v217
	v_mul_f32_e32 v218, 0x3fb8aa3b, v218
	v_mul_f32_e32 v219, 0x3fb8aa3b, v219
	v_exp_f32_e32 v218, v218
	v_exp_f32_e32 v219, v219
	v_add_f32_e32 v218, 1.0, v218
	v_add_f32_e32 v219, 1.0, v219
	v_rcp_f32_e32 v218, v218
	v_rcp_f32_e32 v219, v219
	v_mul_f32_e32 v216, v214, v218
	v_mul_f32_e32 v217, v215, v219
	v_mul_f32_e32 v158, v158, v216
	v_mul_f32_e32 v159, v159, v217
	v_fma_f32 v214, v68, v152, v76
	v_fma_f32 v215, v69, v153, v77
	v_fmac_f32_dpp v214, v152, v52 row_shr:1 row_mask:0xf bank_mask:0xf
	v_fmac_f32_dpp v215, v153, v53 row_shr:1 row_mask:0xf bank_mask:0xf
	v_fmac_f32_dpp v214, v164, v52 row_shl:15 row_mask:0xf bank_mask:0xf
	v_fmac_f32_dpp v215, v165, v53 row_shl:15 row_mask:0xf bank_mask:0xf
	v_fmac_f32_dpp v214, v152, v44 row_shr:2 row_mask:0xf bank_mask:0xf
	v_fmac_f32_dpp v215, v153, v45 row_shr:2 row_mask:0xf bank_mask:0xf
	v_fmac_f32_dpp v214, v164, v44 row_shl:14 row_mask:0xf bank_mask:0xf
	v_fmac_f32_dpp v215, v165, v45 row_shl:14 row_mask:0xf bank_mask:0xf
	v_mul_f32_e32 v216, 0x3d372713, v214
	v_mul_f32_e32 v217, 0x3d372713, v215
	v_mul_f32_e32 v218, 0x3fcc422a, v214
	v_mul_f32_e32 v219, 0x3fcc422a, v215
	v_fma_f32 v216, v214, v216, 1.0
	v_fma_f32 v217, v215, v217, 1.0
	v_mul_f32_e64 v218, v218, -v216
	v_mul_f32_e64 v219, v219, -v217
	v_mul_f32_e32 v218, 0x3fb8aa3b, v218
	v_mul_f32_e32 v219, 0x3fb8aa3b, v219
	v_exp_f32_e32 v218, v218
	v_exp_f32_e32 v219, v219
	v_add_f32_e32 v218, 1.0, v218
	v_add_f32_e32 v219, 1.0, v219
	v_rcp_f32_e32 v218, v218
	v_rcp_f32_e32 v219, v219
	v_mul_f32_e32 v216, v214, v218
	v_mul_f32_e32 v217, v215, v219
	v_mul_f32_e32 v160, v160, v216
	v_mul_f32_e32 v161, v161, v217
	v_fma_f32 v214, v70, v146, v78
	v_fma_f32 v215, v71, v147, v79
	v_fmac_f32_dpp v214, v146, v54 row_shr:1 row_mask:0xf bank_mask:0xf
	v_fmac_f32_dpp v215, v147, v55 row_shr:1 row_mask:0xf bank_mask:0xf
	v_fmac_f32_dpp v214, v166, v54 row_shl:15 row_mask:0xf bank_mask:0xf
	v_fmac_f32_dpp v215, v167, v55 row_shl:15 row_mask:0xf bank_mask:0xf
	v_fmac_f32_dpp v214, v146, v46 row_shr:2 row_mask:0xf bank_mask:0xf
	v_fmac_f32_dpp v215, v147, v47 row_shr:2 row_mask:0xf bank_mask:0xf
	v_fmac_f32_dpp v214, v166, v46 row_shl:14 row_mask:0xf bank_mask:0xf
	v_fmac_f32_dpp v215, v167, v47 row_shl:14 row_mask:0xf bank_mask:0xf
	v_mul_f32_e32 v216, 0x3d372713, v214
	v_mul_f32_e32 v217, 0x3d372713, v215
	v_mul_f32_e32 v218, 0x3fcc422a, v214
	v_mul_f32_e32 v219, 0x3fcc422a, v215
	v_fma_f32 v216, v214, v216, 1.0
	v_fma_f32 v217, v215, v217, 1.0
	v_mul_f32_e64 v218, v218, -v216
	v_mul_f32_e64 v219, v219, -v217
	v_mul_f32_e32 v218, 0x3fb8aa3b, v218
	v_mul_f32_e32 v219, 0x3fb8aa3b, v219
	v_exp_f32_e32 v218, v218
	v_exp_f32_e32 v219, v219
	v_add_f32_e32 v218, 1.0, v218
	v_add_f32_e32 v219, 1.0, v219
	v_rcp_f32_e32 v218, v218
	v_rcp_f32_e32 v219, v219
	v_mul_f32_e32 v216, v214, v218
	v_mul_f32_e32 v217, v215, v219
	v_mul_f32_e32 v154, v154, v216
	v_mul_f32_e32 v155, v155, v217
	v_fma_f32 v214, v72, v148, v80
	v_fma_f32 v215, v73, v149, v81
	v_fmac_f32_dpp v214, v148, v56 row_shr:1 row_mask:0xf bank_mask:0xf
	v_fmac_f32_dpp v215, v149, v57 row_shr:1 row_mask:0xf bank_mask:0xf
	v_fmac_f32_dpp v214, v168, v56 row_shl:15 row_mask:0xf bank_mask:0xf
	v_fmac_f32_dpp v215, v169, v57 row_shl:15 row_mask:0xf bank_mask:0xf
	v_fmac_f32_dpp v214, v148, v48 row_shr:2 row_mask:0xf bank_mask:0xf
	v_fmac_f32_dpp v215, v149, v49 row_shr:2 row_mask:0xf bank_mask:0xf
	v_fmac_f32_dpp v214, v168, v48 row_shl:14 row_mask:0xf bank_mask:0xf
	v_fmac_f32_dpp v215, v169, v49 row_shl:14 row_mask:0xf bank_mask:0xf
	v_mul_f32_e32 v216, 0x3d372713, v214
	v_mul_f32_e32 v217, 0x3d372713, v215
	v_mul_f32_e32 v218, 0x3fcc422a, v214
	v_mul_f32_e32 v219, 0x3fcc422a, v215
	v_fma_f32 v216, v214, v216, 1.0
	v_fma_f32 v217, v215, v217, 1.0
	v_mul_f32_e64 v218, v218, -v216
	v_mul_f32_e64 v219, v219, -v217
	v_mul_f32_e32 v218, 0x3fb8aa3b, v218
	v_mul_f32_e32 v219, 0x3fb8aa3b, v219
	v_exp_f32_e32 v218, v218
	v_exp_f32_e32 v219, v219
	v_add_f32_e32 v218, 1.0, v218
	v_add_f32_e32 v219, 1.0, v219
	v_rcp_f32_e32 v218, v218
	v_rcp_f32_e32 v219, v219
	v_mul_f32_e32 v216, v214, v218
	v_mul_f32_e32 v217, v215, v219
	v_mul_f32_e32 v156, v156, v216
	v_mul_f32_e32 v157, v157, v217
	v_cvt_pk_bf16_f32 v158, v158, v159
	v_cvt_pk_bf16_f32 v159, v160, v161
	v_cvt_pk_bf16_f32 v160, v154, v155
	v_cvt_pk_bf16_f32 v161, v156, v157
	v_mov_b32_e32 v222, v195
	global_store_dwordx4 v222, v[158:161], s[70:71]
	s_add_u32 s86, s74, 0x10000
	s_addc_u32 s87, s75, 0
	global_load_dwordx4 v[162:165], v196, s[86:87]
	global_load_dwordx4 v[166:169], v196, s[86:87] offset:16
	s_add_u32 s86, s72, 0x10000
	s_addc_u32 s87, s73, 0
	s_mov_b32 exec_lo, 0xc000c000
	s_mov_b32 exec_hi, 0xc000c000
	global_store_dwordx4 v196, v[134:137], s[86:87]
	global_store_dwordx4 v196, v[130:133], s[86:87] offset:16
	s_mov_b64 exec, -1
	s_waitcnt vmcnt(2)
; #define PG8_LAS __attribute__((address_space(3)))
;     __device__ __forceinline__ void operator()(const f32x4 (&acc)[2][2][4][2], const Unit& u, int wr, int wc, int fr, int fq) const {
;     ...
;                 if (samp) {
;                     const int bs = (row - MP) >> 4;
; #pragma unroll
;                     for (int n = 0; n < 2; ++n) { const f32x4 s0 = *(const f32x4*)(state + ((size_t)bs * 2 + 0) * DFF + cgc + 4 * n), s1 = *(const f32x4*)(state + ((size_t)bs * 2 + 1) * DFF + cgc + 4 * n);
;                         w1[n] = s1; w2[n] = fr == 0 ? s0 : s1; }
;                 } else if (m == 0) {
;                     if (blk > 0) {
; #pragma unroll
;                         for (int n = 0; n < 2; ++n) { const f32x4 c14 = *(const PG8_LAS f32x4*)(xbuf + ((blk - 1) * 2 + 0) * 128 + cl + 4 * n), c15 = *(const PG8_LAS f32x4*)(xbuf + ((blk - 1) * 2 + 1) * 128 + cl + 4 * n);
;                             w1[n] = c15; w2[n] = fr == 0 ? c14 : c15; }
;                     } else { w1[0] = w1[1] = w2[0] = w2[1] = (f32x4){0.f, 0.f, 0.f, 0.f}; }
;                 } else {
; #pragma unroll
;                     for (int n = 0; n < 2; ++n)
; #pragma unroll
;                         for (int i = 0; i < 4; ++i) { const float ap = acc[ai][0][m - 1][n][i]; w1[n][i] = dppf<0x10F>(ap); w2[n][i] = dppf<0x10E>(ap); }
;                 }
;                 f32x4 hv[2];
; #pragma unroll
;                 for (int n = 0; n < 2; ++n) {
;                     const f32x4 a = acc[ai][0][m][n], b = acc[ai][1][m][n];
; #pragma unroll
;                     for (int i = 0; i < 4; ++i) {
;                         const float s1 = dppf<0x111>(a[i]), s2 = dppf<0x112>(a[i]);
;                         const float p1 = fr >= 1 ? s1 : w1[n][i], p2 = fr >= 2 ? s2 : w2[n][i];
;                         const float ac = cw0[n][i] * p2 + cw1[n][i] * p1 + cw2[n][i] * a[i] + cb[n][i];
;                         hv[n][i] = gelu_tanh(ac) * b[i];
;                     }
;                 }
;                 *(u32x4*)(hh + (size_t)row * DFF + cgc) = pack8(hv[0], hv[1]);
;                 if (samp) {
;                     if (fr >= 14) { const int bs = (row - MP) >> 4; float* p = out + O_CVS + ((size_t)bs * 2 + (fr - 14)) * DFF + cgc; *(f32x4*)p = acc[ai][0][m][0]; *(f32x4*)(p + 4) = acc[ai][0][m][1]; }
	v_fma_f32 v214, v66, v134, v74
	v_fma_f32 v215, v67, v135, v75
	v_fmac_f32_dpp v214, v134, v50 row_shr:1 row_mask:0xf bank_mask:0xf
	v_fmac_f32_dpp v215, v135, v51 row_shr:1 row_mask:0xf bank_mask:0xf
	v_fmac_f32_dpp v214, v162, v50 row_shl:15 row_mask:0xf bank_mask:0xf
	v_fmac_f32_dpp v215, v163, v51 row_shl:15 row_mask:0xf bank_mask:0xf
	v_fmac_f32_dpp v214, v134, v42 row_shr:2 row_mask:0xf bank_mask:0xf
	v_fmac_f32_dpp v215, v135, v43 row_shr:2 row_mask:0xf bank_mask:0xf
	v_fmac_f32_dpp v214, v162, v42 row_shl:14 row_mask:0xf bank_mask:0xf
	v_fmac_f32_dpp v215, v163, v43 row_shl:14 row_mask:0xf bank_mask:0xf
	v_mul_f32_e32 v216, 0x3d372713, v214
	v_mul_f32_e32 v217, 0x3d372713, v215
	v_mul_f32_e32 v218, 0x3fcc422a, v214
	v_mul_f32_e32 v219, 0x3fcc422a, v215
	v_fma_f32 v216, v214, v216, 1.0
	v_fma_f32 v217, v215, v217, 1.0
	v_mul_f32_e64 v218, v218, -v216
	v_mul_f32_e64 v219, v219, -v217
	v_mul_f32_e32 v218, 0x3fb8aa3b, v218
	v_mul_f32_e32 v219, 0x3fb8aa3b, v219
	v_exp_f32_e32 v218, v218
	v_exp_f32_e32 v219, v219
	v_add_f32_e32 v218, 1.0, v218
	v_add_f32_e32 v219, 1.0, v219
	v_rcp_f32_e32 v218, v218
	v_rcp_f32_e32 v219, v219
	v_mul_f32_e32 v216, v214, v218
	v_mul_f32_e32 v217, v215, v219
	v_mul_f32_e32 v142, v142, v216
	v_mul_f32_e32 v143, v143, v217
	v_fma_f32 v214, v68, v136, v76
	v_fma_f32 v215, v69, v137, v77
	v_fmac_f32_dpp v214, v136, v52 row_shr:1 row_mask:0xf bank_mask:0xf
	v_fmac_f32_dpp v215, v137, v53 row_shr:1 row_mask:0xf bank_mask:0xf
	v_fmac_f32_dpp v214, v164, v52 row_shl:15 row_mask:0xf bank_mask:0xf
	v_fmac_f32_dpp v215, v165, v53 row_shl:15 row_mask:0xf bank_mask:0xf
	v_fmac_f32_dpp v214, v136, v44 row_shr:2 row_mask:0xf bank_mask:0xf
	v_fmac_f32_dpp v215, v137, v45 row_shr:2 row_mask:0xf bank_mask:0xf
	v_fmac_f32_dpp v214, v164, v44 row_shl:14 row_mask:0xf bank_mask:0xf
	v_fmac_f32_dpp v215, v165, v45 row_shl:14 row_mask:0xf bank_mask:0xf
	v_mul_f32_e32 v216, 0x3d372713, v214
	v_mul_f32_e32 v217, 0x3d372713, v215
	v_mul_f32_e32 v218, 0x3fcc422a, v214
	v_mul_f32_e32 v219, 0x3fcc422a, v215
	v_fma_f32 v216, v214, v216, 1.0
	v_fma_f32 v217, v215, v217, 1.0
	v_mul_f32_e64 v218, v218, -v216
	v_mul_f32_e64 v219, v219, -v217
	v_mul_f32_e32 v218, 0x3fb8aa3b, v218
	v_mul_f32_e32 v219, 0x3fb8aa3b, v219
	v_exp_f32_e32 v218, v218
	v_exp_f32_e32 v219, v219
	v_add_f32_e32 v218, 1.0, v218
	v_add_f32_e32 v219, 1.0, v219
	v_rcp_f32_e32 v218, v218
	v_rcp_f32_e32 v219, v219
	v_mul_f32_e32 v216, v214, v218
	v_mul_f32_e32 v217, v215, v219
	v_mul_f32_e32 v144, v144, v216
	v_mul_f32_e32 v145, v145, v217
	v_fma_f32 v214, v70, v130, v78
	v_fma_f32 v215, v71, v131, v79
	v_fmac_f32_dpp v214, v130, v54 row_shr:1 row_mask:0xf bank_mask:0xf
	v_fmac_f32_dpp v215, v131, v55 row_shr:1 row_mask:0xf bank_mask:0xf
	v_fmac_f32_dpp v214, v166, v54 row_shl:15 row_mask:0xf bank_mask:0xf
	v_fmac_f32_dpp v215, v167, v55 row_shl:15 row_mask:0xf bank_mask:0xf
	v_fmac_f32_dpp v214, v130, v46 row_shr:2 row_mask:0xf bank_mask:0xf
	v_fmac_f32_dpp v215, v131, v47 row_shr:2 row_mask:0xf bank_mask:0xf
	v_fmac_f32_dpp v214, v166, v46 row_shl:14 row_mask:0xf bank_mask:0xf
	v_fmac_f32_dpp v215, v167, v47 row_shl:14 row_mask:0xf bank_mask:0xf
	v_mul_f32_e32 v216, 0x3d372713, v214
	v_mul_f32_e32 v217, 0x3d372713, v215
	v_mul_f32_e32 v218, 0x3fcc422a, v214
	v_mul_f32_e32 v219, 0x3fcc422a, v215
	v_fma_f32 v216, v214, v216, 1.0
	v_fma_f32 v217, v215, v217, 1.0
	v_mul_f32_e64 v218, v218, -v216
	v_mul_f32_e64 v219, v219, -v217
	v_mul_f32_e32 v218, 0x3fb8aa3b, v218
	v_mul_f32_e32 v219, 0x3fb8aa3b, v219
	v_exp_f32_e32 v218, v218
	v_exp_f32_e32 v219, v219
	v_add_f32_e32 v218, 1.0, v218
	v_add_f32_e32 v219, 1.0, v219
	v_rcp_f32_e32 v218, v218
	v_rcp_f32_e32 v219, v219
	v_mul_f32_e32 v216, v214, v218
	v_mul_f32_e32 v217, v215, v219
	v_mul_f32_e32 v138, v138, v216
	v_mul_f32_e32 v139, v139, v217
	v_fma_f32 v214, v72, v132, v80
	v_fma_f32 v215, v73, v133, v81
	v_fmac_f32_dpp v214, v132, v56 row_shr:1 row_mask:0xf bank_mask:0xf
	v_fmac_f32_dpp v215, v133, v57 row_shr:1 row_mask:0xf bank_mask:0xf
	v_fmac_f32_dpp v214, v168, v56 row_shl:15 row_mask:0xf bank_mask:0xf
	v_fmac_f32_dpp v215, v169, v57 row_shl:15 row_mask:0xf bank_mask:0xf
	v_fmac_f32_dpp v214, v132, v48 row_shr:2 row_mask:0xf bank_mask:0xf
	v_fmac_f32_dpp v215, v133, v49 row_shr:2 row_mask:0xf bank_mask:0xf
	v_fmac_f32_dpp v214, v168, v48 row_shl:14 row_mask:0xf bank_mask:0xf
	v_fmac_f32_dpp v215, v169, v49 row_shl:14 row_mask:0xf bank_mask:0xf
	v_mul_f32_e32 v216, 0x3d372713, v214
	v_mul_f32_e32 v217, 0x3d372713, v215
	v_mul_f32_e32 v218, 0x3fcc422a, v214
	v_mul_f32_e32 v219, 0x3fcc422a, v215
	v_fma_f32 v216, v214, v216, 1.0
	v_fma_f32 v217, v215, v217, 1.0
	v_mul_f32_e64 v218, v218, -v216
	v_mul_f32_e64 v219, v219, -v217
	v_mul_f32_e32 v218, 0x3fb8aa3b, v218
	v_mul_f32_e32 v219, 0x3fb8aa3b, v219
	v_exp_f32_e32 v218, v218
	v_exp_f32_e32 v219, v219
	v_add_f32_e32 v218, 1.0, v218
	v_add_f32_e32 v219, 1.0, v219
	v_rcp_f32_e32 v218, v218
	v_rcp_f32_e32 v219, v219
	v_mul_f32_e32 v216, v214, v218
	v_mul_f32_e32 v217, v215, v219
	v_mul_f32_e32 v140, v140, v216
	v_mul_f32_e32 v141, v141, v217
	v_cvt_pk_bf16_f32 v142, v142, v143
	v_cvt_pk_bf16_f32 v143, v144, v145
	v_cvt_pk_bf16_f32 v144, v138, v139
	v_cvt_pk_bf16_f32 v145, v140, v141
	v_add_u32_e32 v222, 0x40000, v195
	global_store_dwordx4 v222, v[142:145], s[70:71]
	s_add_u32 s86, s74, 0x20000
	s_addc_u32 s87, s75, 0
	global_load_dwordx4 v[162:165], v196, s[86:87]
	global_load_dwordx4 v[166:169], v196, s[86:87] offset:16
	s_add_u32 s86, s72, 0x20000
	s_addc_u32 s87, s73, 0
	s_mov_b32 exec_lo, 0xc000c000
	s_mov_b32 exec_hi, 0xc000c000
	global_store_dwordx4 v196, v[118:121], s[86:87]
	global_store_dwordx4 v196, v[114:117], s[86:87] offset:16
	s_mov_b64 exec, -1
	s_waitcnt vmcnt(2)
; #define PG8_LAS __attribute__((address_space(3)))
;     __device__ __forceinline__ void operator()(const f32x4 (&acc)[2][2][4][2], const Unit& u, int wr, int wc, int fr, int fq) const {
;     ...
;                 if (samp) {
;                     const int bs = (row - MP) >> 4;
; #pragma unroll
;                     for (int n = 0; n < 2; ++n) { const f32x4 s0 = *(const f32x4*)(state + ((size_t)bs * 2 + 0) * DFF + cgc + 4 * n), s1 = *(const f32x4*)(state + ((size_t)bs * 2 + 1) * DFF + cgc + 4 * n);
;                         w1[n] = s1; w2[n] = fr == 0 ? s0 : s1; }
;                 } else if (m == 0) {
;                     if (blk > 0) {
; #pragma unroll
;                         for (int n = 0; n < 2; ++n) { const f32x4 c14 = *(const PG8_LAS f32x4*)(xbuf + ((blk - 1) * 2 + 0) * 128 + cl + 4 * n), c15 = *(const PG8_LAS f32x4*)(xbuf + ((blk - 1) * 2 + 1) * 128 + cl + 4 * n);
;                             w1[n] = c15; w2[n] = fr == 0 ? c14 : c15; }
;                     } else { w1[0] = w1[1] = w2[0] = w2[1] = (f32x4){0.f, 0.f, 0.f, 0.f}; }
;                 } else {
; #pragma unroll
;                     for (int n = 0; n < 2; ++n)
; #pragma unroll
;                         for (int i = 0; i < 4; ++i) { const float ap = acc[ai][0][m - 1][n][i]; w1[n][i] = dppf<0x10F>(ap); w2[n][i] = dppf<0x10E>(ap); }
;                 }
;                 f32x4 hv[2];
; #pragma unroll
;                 for (int n = 0; n < 2; ++n) {
;                     const f32x4 a = acc[ai][0][m][n], b = acc[ai][1][m][n];
; #pragma unroll
;                     for (int i = 0; i < 4; ++i) {
;                         const float s1 = dppf<0x111>(a[i]), s2 = dppf<0x112>(a[i]);
;                         const float p1 = fr >= 1 ? s1 : w1[n][i], p2 = fr >= 2 ? s2 : w2[n][i];
;                         const float ac = cw0[n][i] * p2 + cw1[n][i] * p1 + cw2[n][i] * a[i] + cb[n][i];
;                         hv[n][i] = gelu_tanh(ac) * b[i];
;                     }
;                 }
;                 *(u32x4*)(hh + (size_t)row * DFF + cgc) = pack8(hv[0], hv[1]);
;                 if (samp) {
;                     if (fr >= 14) { const int bs = (row - MP) >> 4; float* p = out + O_CVS + ((size_t)bs * 2 + (fr - 14)) * DFF + cgc; *(f32x4*)p = acc[ai][0][m][0]; *(f32x4*)(p + 4) = acc[ai][0][m][1]; }
	v_fma_f32 v214, v66, v118, v74
	v_fma_f32 v215, v67, v119, v75
	v_fmac_f32_dpp v214, v118, v50 row_shr:1 row_mask:0xf bank_mask:0xf
	v_fmac_f32_dpp v215, v119, v51 row_shr:1 row_mask:0xf bank_mask:0xf
	v_fmac_f32_dpp v214, v162, v50 row_shl:15 row_mask:0xf bank_mask:0xf
	v_fmac_f32_dpp v215, v163, v51 row_shl:15 row_mask:0xf bank_mask:0xf
	v_fmac_f32_dpp v214, v118, v42 row_shr:2 row_mask:0xf bank_mask:0xf
	v_fmac_f32_dpp v215, v119, v43 row_shr:2 row_mask:0xf bank_mask:0xf
	v_fmac_f32_dpp v214, v162, v42 row_shl:14 row_mask:0xf bank_mask:0xf
	v_fmac_f32_dpp v215, v163, v43 row_shl:14 row_mask:0xf bank_mask:0xf
	v_mul_f32_e32 v216, 0x3d372713, v214
	v_mul_f32_e32 v217, 0x3d372713, v215
	v_mul_f32_e32 v218, 0x3fcc422a, v214
	v_mul_f32_e32 v219, 0x3fcc422a, v215
	v_fma_f32 v216, v214, v216, 1.0
	v_fma_f32 v217, v215, v217, 1.0
	v_mul_f32_e64 v218, v218, -v216
	v_mul_f32_e64 v219, v219, -v217
	v_mul_f32_e32 v218, 0x3fb8aa3b, v218
	v_mul_f32_e32 v219, 0x3fb8aa3b, v219
	v_exp_f32_e32 v218, v218
	v_exp_f32_e32 v219, v219
	v_add_f32_e32 v218, 1.0, v218
	v_add_f32_e32 v219, 1.0, v219
	v_rcp_f32_e32 v218, v218
	v_rcp_f32_e32 v219, v219
	v_mul_f32_e32 v216, v214, v218
	v_mul_f32_e32 v217, v215, v219
	v_mul_f32_e32 v126, v126, v216
	v_mul_f32_e32 v127, v127, v217
	v_fma_f32 v214, v68, v120, v76
	v_fma_f32 v215, v69, v121, v77
	v_fmac_f32_dpp v214, v120, v52 row_shr:1 row_mask:0xf bank_mask:0xf
	v_fmac_f32_dpp v215, v121, v53 row_shr:1 row_mask:0xf bank_mask:0xf
	v_fmac_f32_dpp v214, v164, v52 row_shl:15 row_mask:0xf bank_mask:0xf
	v_fmac_f32_dpp v215, v165, v53 row_shl:15 row_mask:0xf bank_mask:0xf
	v_fmac_f32_dpp v214, v120, v44 row_shr:2 row_mask:0xf bank_mask:0xf
	v_fmac_f32_dpp v215, v121, v45 row_shr:2 row_mask:0xf bank_mask:0xf
	v_fmac_f32_dpp v214, v164, v44 row_shl:14 row_mask:0xf bank_mask:0xf
	v_fmac_f32_dpp v215, v165, v45 row_shl:14 row_mask:0xf bank_mask:0xf
	v_mul_f32_e32 v216, 0x3d372713, v214
	v_mul_f32_e32 v217, 0x3d372713, v215
	v_mul_f32_e32 v218, 0x3fcc422a, v214
	v_mul_f32_e32 v219, 0x3fcc422a, v215
	v_fma_f32 v216, v214, v216, 1.0
	v_fma_f32 v217, v215, v217, 1.0
	v_mul_f32_e64 v218, v218, -v216
	v_mul_f32_e64 v219, v219, -v217
	v_mul_f32_e32 v218, 0x3fb8aa3b, v218
	v_mul_f32_e32 v219, 0x3fb8aa3b, v219
	v_exp_f32_e32 v218, v218
	v_exp_f32_e32 v219, v219
	v_add_f32_e32 v218, 1.0, v218
	v_add_f32_e32 v219, 1.0, v219
	v_rcp_f32_e32 v218, v218
	v_rcp_f32_e32 v219, v219
	v_mul_f32_e32 v216, v214, v218
	v_mul_f32_e32 v217, v215, v219
	v_mul_f32_e32 v128, v128, v216
	v_mul_f32_e32 v129, v129, v217
	v_fma_f32 v214, v70, v114, v78
	v_fma_f32 v215, v71, v115, v79
	v_fmac_f32_dpp v214, v114, v54 row_shr:1 row_mask:0xf bank_mask:0xf
	v_fmac_f32_dpp v215, v115, v55 row_shr:1 row_mask:0xf bank_mask:0xf
	v_fmac_f32_dpp v214, v166, v54 row_shl:15 row_mask:0xf bank_mask:0xf
	v_fmac_f32_dpp v215, v167, v55 row_shl:15 row_mask:0xf bank_mask:0xf
	v_fmac_f32_dpp v214, v114, v46 row_shr:2 row_mask:0xf bank_mask:0xf
	v_fmac_f32_dpp v215, v115, v47 row_shr:2 row_mask:0xf bank_mask:0xf
	v_fmac_f32_dpp v214, v166, v46 row_shl:14 row_mask:0xf bank_mask:0xf
	v_fmac_f32_dpp v215, v167, v47 row_shl:14 row_mask:0xf bank_mask:0xf
	v_mul_f32_e32 v216, 0x3d372713, v214
	v_mul_f32_e32 v217, 0x3d372713, v215
	v_mul_f32_e32 v218, 0x3fcc422a, v214
	v_mul_f32_e32 v219, 0x3fcc422a, v215
	v_fma_f32 v216, v214, v216, 1.0
	v_fma_f32 v217, v215, v217, 1.0
	v_mul_f32_e64 v218, v218, -v216
	v_mul_f32_e64 v219, v219, -v217
	v_mul_f32_e32 v218, 0x3fb8aa3b, v218
	v_mul_f32_e32 v219, 0x3fb8aa3b, v219
	v_exp_f32_e32 v218, v218
	v_exp_f32_e32 v219, v219
	v_add_f32_e32 v218, 1.0, v218
	v_add_f32_e32 v219, 1.0, v219
	v_rcp_f32_e32 v218, v218
	v_rcp_f32_e32 v219, v219
	v_mul_f32_e32 v216, v214, v218
	v_mul_f32_e32 v217, v215, v219
	v_mul_f32_e32 v122, v122, v216
	v_mul_f32_e32 v123, v123, v217
	v_fma_f32 v214, v72, v116, v80
	v_fma_f32 v215, v73, v117, v81
	v_fmac_f32_dpp v214, v116, v56 row_shr:1 row_mask:0xf bank_mask:0xf
	v_fmac_f32_dpp v215, v117, v57 row_shr:1 row_mask:0xf bank_mask:0xf
	v_fmac_f32_dpp v214, v168, v56 row_shl:15 row_mask:0xf bank_mask:0xf
	v_fmac_f32_dpp v215, v169, v57 row_shl:15 row_mask:0xf bank_mask:0xf
	v_fmac_f32_dpp v214, v116, v48 row_shr:2 row_mask:0xf bank_mask:0xf
	v_fmac_f32_dpp v215, v117, v49 row_shr:2 row_mask:0xf bank_mask:0xf
	v_fmac_f32_dpp v214, v168, v48 row_shl:14 row_mask:0xf bank_mask:0xf
	v_fmac_f32_dpp v215, v169, v49 row_shl:14 row_mask:0xf bank_mask:0xf
	v_mul_f32_e32 v216, 0x3d372713, v214
	v_mul_f32_e32 v217, 0x3d372713, v215
	v_mul_f32_e32 v218, 0x3fcc422a, v214
	v_mul_f32_e32 v219, 0x3fcc422a, v215
	v_fma_f32 v216, v214, v216, 1.0
	v_fma_f32 v217, v215, v217, 1.0
	v_mul_f32_e64 v218, v218, -v216
	v_mul_f32_e64 v219, v219, -v217
	v_mul_f32_e32 v218, 0x3fb8aa3b, v218
	v_mul_f32_e32 v219, 0x3fb8aa3b, v219
	v_exp_f32_e32 v218, v218
	v_exp_f32_e32 v219, v219
	v_add_f32_e32 v218, 1.0, v218
	v_add_f32_e32 v219, 1.0, v219
	v_rcp_f32_e32 v218, v218
	v_rcp_f32_e32 v219, v219
	v_mul_f32_e32 v216, v214, v218
	v_mul_f32_e32 v217, v215, v219
	v_mul_f32_e32 v124, v124, v216
	v_mul_f32_e32 v125, v125, v217
	v_cvt_pk_bf16_f32 v126, v126, v127
	v_cvt_pk_bf16_f32 v127, v128, v129
	v_cvt_pk_bf16_f32 v128, v122, v123
	v_cvt_pk_bf16_f32 v129, v124, v125
	v_add_u32_e32 v222, 0x80000, v195
	global_store_dwordx4 v222, v[126:129], s[70:71]
	s_add_u32 s86, s74, 0x30000
	s_addc_u32 s87, s75, 0
	global_load_dwordx4 v[162:165], v196, s[86:87]
	global_load_dwordx4 v[166:169], v196, s[86:87] offset:16
	s_add_u32 s86, s72, 0x30000
	s_addc_u32 s87, s73, 0
	s_mov_b32 exec_lo, 0xc000c000
	s_mov_b32 exec_hi, 0xc000c000
	global_store_dwordx4 v196, v[102:105], s[86:87]
	global_store_dwordx4 v196, v[98:101], s[86:87] offset:16
	s_mov_b64 exec, -1
	s_waitcnt vmcnt(2)
; #define PG8_LAS __attribute__((address_space(3)))
;     __device__ __forceinline__ void operator()(const f32x4 (&acc)[2][2][4][2], const Unit& u, int wr, int wc, int fr, int fq) const {
;     ...
;                 if (samp) {
;                     const int bs = (row - MP) >> 4;
; #pragma unroll
;                     for (int n = 0; n < 2; ++n) { const f32x4 s0 = *(const f32x4*)(state + ((size_t)bs * 2 + 0) * DFF + cgc + 4 * n), s1 = *(const f32x4*)(state + ((size_t)bs * 2 + 1) * DFF + cgc + 4 * n);
;                         w1[n] = s1; w2[n] = fr == 0 ? s0 : s1; }
;                 } else if (m == 0) {
;                     if (blk > 0) {
; #pragma unroll
;                         for (int n = 0; n < 2; ++n) { const f32x4 c14 = *(const PG8_LAS f32x4*)(xbuf + ((blk - 1) * 2 + 0) * 128 + cl + 4 * n), c15 = *(const PG8_LAS f32x4*)(xbuf + ((blk - 1) * 2 + 1) * 128 + cl + 4 * n);
;                             w1[n] = c15; w2[n] = fr == 0 ? c14 : c15; }
;                     } else { w1[0] = w1[1] = w2[0] = w2[1] = (f32x4){0.f, 0.f, 0.f, 0.f}; }
;                 } else {
; #pragma unroll
;                     for (int n = 0; n < 2; ++n)
; #pragma unroll
;                         for (int i = 0; i < 4; ++i) { const float ap = acc[ai][0][m - 1][n][i]; w1[n][i] = dppf<0x10F>(ap); w2[n][i] = dppf<0x10E>(ap); }
;                 }
;                 f32x4 hv[2];
; #pragma unroll
;                 for (int n = 0; n < 2; ++n) {
;                     const f32x4 a = acc[ai][0][m][n], b = acc[ai][1][m][n];
; #pragma unroll
;                     for (int i = 0; i < 4; ++i) {
;                         const float s1 = dppf<0x111>(a[i]), s2 = dppf<0x112>(a[i]);
;                         const float p1 = fr >= 1 ? s1 : w1[n][i], p2 = fr >= 2 ? s2 : w2[n][i];
;                         const float ac = cw0[n][i] * p2 + cw1[n][i] * p1 + cw2[n][i] * a[i] + cb[n][i];
;                         hv[n][i] = gelu_tanh(ac) * b[i];
;                     }
;                 }
;                 *(u32x4*)(hh + (size_t)row * DFF + cgc) = pack8(hv[0], hv[1]);
;                 if (samp) {
;                     if (fr >= 14) { const int bs = (row - MP) >> 4; float* p = out + O_CVS + ((size_t)bs * 2 + (fr - 14)) * DFF + cgc; *(f32x4*)p = acc[ai][0][m][0]; *(f32x4*)(p + 4) = acc[ai][0][m][1]; }
	v_fma_f32 v214, v66, v102, v74
	v_fma_f32 v215, v67, v103, v75
	v_fmac_f32_dpp v214, v102, v50 row_shr:1 row_mask:0xf bank_mask:0xf
	v_fmac_f32_dpp v215, v103, v51 row_shr:1 row_mask:0xf bank_mask:0xf
	v_fmac_f32_dpp v214, v162, v50 row_shl:15 row_mask:0xf bank_mask:0xf
	v_fmac_f32_dpp v215, v163, v51 row_shl:15 row_mask:0xf bank_mask:0xf
	v_fmac_f32_dpp v214, v102, v42 row_shr:2 row_mask:0xf bank_mask:0xf
	v_fmac_f32_dpp v215, v103, v43 row_shr:2 row_mask:0xf bank_mask:0xf
	v_fmac_f32_dpp v214, v162, v42 row_shl:14 row_mask:0xf bank_mask:0xf
	v_fmac_f32_dpp v215, v163, v43 row_shl:14 row_mask:0xf bank_mask:0xf
	v_mul_f32_e32 v216, 0x3d372713, v214
	v_mul_f32_e32 v217, 0x3d372713, v215
	v_mul_f32_e32 v218, 0x3fcc422a, v214
	v_mul_f32_e32 v219, 0x3fcc422a, v215
	v_fma_f32 v216, v214, v216, 1.0
	v_fma_f32 v217, v215, v217, 1.0
	v_mul_f32_e64 v218, v218, -v216
	v_mul_f32_e64 v219, v219, -v217
	v_mul_f32_e32 v218, 0x3fb8aa3b, v218
	v_mul_f32_e32 v219, 0x3fb8aa3b, v219
	v_exp_f32_e32 v218, v218
	v_exp_f32_e32 v219, v219
	v_add_f32_e32 v218, 1.0, v218
	v_add_f32_e32 v219, 1.0, v219
	v_rcp_f32_e32 v218, v218
	v_rcp_f32_e32 v219, v219
	v_mul_f32_e32 v216, v214, v218
	v_mul_f32_e32 v217, v215, v219
	v_mul_f32_e32 v110, v110, v216
	v_mul_f32_e32 v111, v111, v217
	v_fma_f32 v214, v68, v104, v76
	v_fma_f32 v215, v69, v105, v77
	v_fmac_f32_dpp v214, v104, v52 row_shr:1 row_mask:0xf bank_mask:0xf
	v_fmac_f32_dpp v215, v105, v53 row_shr:1 row_mask:0xf bank_mask:0xf
	v_fmac_f32_dpp v214, v164, v52 row_shl:15 row_mask:0xf bank_mask:0xf
	v_fmac_f32_dpp v215, v165, v53 row_shl:15 row_mask:0xf bank_mask:0xf
	v_fmac_f32_dpp v214, v104, v44 row_shr:2 row_mask:0xf bank_mask:0xf
	v_fmac_f32_dpp v215, v105, v45 row_shr:2 row_mask:0xf bank_mask:0xf
	v_fmac_f32_dpp v214, v164, v44 row_shl:14 row_mask:0xf bank_mask:0xf
	v_fmac_f32_dpp v215, v165, v45 row_shl:14 row_mask:0xf bank_mask:0xf
	v_mul_f32_e32 v216, 0x3d372713, v214
	v_mul_f32_e32 v217, 0x3d372713, v215
	v_mul_f32_e32 v218, 0x3fcc422a, v214
	v_mul_f32_e32 v219, 0x3fcc422a, v215
	v_fma_f32 v216, v214, v216, 1.0
	v_fma_f32 v217, v215, v217, 1.0
	v_mul_f32_e64 v218, v218, -v216
	v_mul_f32_e64 v219, v219, -v217
	v_mul_f32_e32 v218, 0x3fb8aa3b, v218
	v_mul_f32_e32 v219, 0x3fb8aa3b, v219
	v_exp_f32_e32 v218, v218
	v_exp_f32_e32 v219, v219
	v_add_f32_e32 v218, 1.0, v218
	v_add_f32_e32 v219, 1.0, v219
	v_rcp_f32_e32 v218, v218
	v_rcp_f32_e32 v219, v219
	v_mul_f32_e32 v216, v214, v218
	v_mul_f32_e32 v217, v215, v219
	v_mul_f32_e32 v112, v112, v216
	v_mul_f32_e32 v113, v113, v217
	v_fma_f32 v214, v70, v98, v78
	v_fma_f32 v215, v71, v99, v79
	v_fmac_f32_dpp v214, v98, v54 row_shr:1 row_mask:0xf bank_mask:0xf
	v_fmac_f32_dpp v215, v99, v55 row_shr:1 row_mask:0xf bank_mask:0xf
	v_fmac_f32_dpp v214, v166, v54 row_shl:15 row_mask:0xf bank_mask:0xf
	v_fmac_f32_dpp v215, v167, v55 row_shl:15 row_mask:0xf bank_mask:0xf
	v_fmac_f32_dpp v214, v98, v46 row_shr:2 row_mask:0xf bank_mask:0xf
	v_fmac_f32_dpp v215, v99, v47 row_shr:2 row_mask:0xf bank_mask:0xf
	v_fmac_f32_dpp v214, v166, v46 row_shl:14 row_mask:0xf bank_mask:0xf
	v_fmac_f32_dpp v215, v167, v47 row_shl:14 row_mask:0xf bank_mask:0xf
	v_mul_f32_e32 v216, 0x3d372713, v214
	v_mul_f32_e32 v217, 0x3d372713, v215
	v_mul_f32_e32 v218, 0x3fcc422a, v214
	v_mul_f32_e32 v219, 0x3fcc422a, v215
	v_fma_f32 v216, v214, v216, 1.0
	v_fma_f32 v217, v215, v217, 1.0
	v_mul_f32_e64 v218, v218, -v216
	v_mul_f32_e64 v219, v219, -v217
	v_mul_f32_e32 v218, 0x3fb8aa3b, v218
	v_mul_f32_e32 v219, 0x3fb8aa3b, v219
	v_exp_f32_e32 v218, v218
	v_exp_f32_e32 v219, v219
	v_add_f32_e32 v218, 1.0, v218
	v_add_f32_e32 v219, 1.0, v219
	v_rcp_f32_e32 v218, v218
	v_rcp_f32_e32 v219, v219
	v_mul_f32_e32 v216, v214, v218
	v_mul_f32_e32 v217, v215, v219
	v_mul_f32_e32 v106, v106, v216
	v_mul_f32_e32 v107, v107, v217
	v_fma_f32 v214, v72, v100, v80
	v_fma_f32 v215, v73, v101, v81
	v_fmac_f32_dpp v214, v100, v56 row_shr:1 row_mask:0xf bank_mask:0xf
	v_fmac_f32_dpp v215, v101, v57 row_shr:1 row_mask:0xf bank_mask:0xf
	v_fmac_f32_dpp v214, v168, v56 row_shl:15 row_mask:0xf bank_mask:0xf
	v_fmac_f32_dpp v215, v169, v57 row_shl:15 row_mask:0xf bank_mask:0xf
	v_fmac_f32_dpp v214, v100, v48 row_shr:2 row_mask:0xf bank_mask:0xf
	v_fmac_f32_dpp v215, v101, v49 row_shr:2 row_mask:0xf bank_mask:0xf
	v_fmac_f32_dpp v214, v168, v48 row_shl:14 row_mask:0xf bank_mask:0xf
	v_fmac_f32_dpp v215, v169, v49 row_shl:14 row_mask:0xf bank_mask:0xf
	v_mul_f32_e32 v216, 0x3d372713, v214
	v_mul_f32_e32 v217, 0x3d372713, v215
	v_mul_f32_e32 v218, 0x3fcc422a, v214
	v_mul_f32_e32 v219, 0x3fcc422a, v215
	v_fma_f32 v216, v214, v216, 1.0
	v_fma_f32 v217, v215, v217, 1.0
	v_mul_f32_e64 v218, v218, -v216
	v_mul_f32_e64 v219, v219, -v217
	v_mul_f32_e32 v218, 0x3fb8aa3b, v218
	v_mul_f32_e32 v219, 0x3fb8aa3b, v219
	v_exp_f32_e32 v218, v218
	v_exp_f32_e32 v219, v219
	v_add_f32_e32 v218, 1.0, v218
	v_add_f32_e32 v219, 1.0, v219
	v_rcp_f32_e32 v218, v218
	v_rcp_f32_e32 v219, v219
	v_mul_f32_e32 v216, v214, v218
	v_mul_f32_e32 v217, v215, v219
	v_mul_f32_e32 v108, v108, v216
	v_mul_f32_e32 v109, v109, v217
	v_cvt_pk_bf16_f32 v110, v110, v111
	v_cvt_pk_bf16_f32 v111, v112, v113
	v_cvt_pk_bf16_f32 v112, v106, v107
	v_cvt_pk_bf16_f32 v113, v108, v109
	v_add_u32_e32 v222, 0xc0000, v195
	global_store_dwordx4 v222, v[110:113], s[70:71]
	s_add_u32 s86, s74, 0x80000
	s_addc_u32 s87, s75, 0
	global_load_dwordx4 v[162:165], v196, s[86:87]
	global_load_dwordx4 v[166:169], v196, s[86:87] offset:16
	s_add_u32 s86, s72, 0x80000
	s_addc_u32 s87, s73, 0
	s_mov_b32 exec_lo, 0xc000c000
	s_mov_b32 exec_hi, 0xc000c000
	global_store_dwordx4 v196, v[86:89], s[86:87]
	global_store_dwordx4 v196, v[82:85], s[86:87] offset:16
	s_mov_b64 exec, -1
	s_waitcnt vmcnt(2)
; #define PG8_LAS __attribute__((address_space(3)))
;     __device__ __forceinline__ void operator()(const f32x4 (&acc)[2][2][4][2], const Unit& u, int wr, int wc, int fr, int fq) const {
;     ...
;                 if (samp) {
;                     const int bs = (row - MP) >> 4;
; #pragma unroll
;                     for (int n = 0; n < 2; ++n) { const f32x4 s0 = *(const f32x4*)(state + ((size_t)bs * 2 + 0) * DFF + cgc + 4 * n), s1 = *(const f32x4*)(state + ((size_t)bs * 2 + 1) * DFF + cgc + 4 * n);
;                         w1[n] = s1; w2[n] = fr == 0 ? s0 : s1; }
;                 } else if (m == 0) {
;                     if (blk > 0) {
; #pragma unroll
;                         for (int n = 0; n < 2; ++n) { const f32x4 c14 = *(const PG8_LAS f32x4*)(xbuf + ((blk - 1) * 2 + 0) * 128 + cl + 4 * n), c15 = *(const PG8_LAS f32x4*)(xbuf + ((blk - 1) * 2 + 1) * 128 + cl + 4 * n);
;                             w1[n] = c15; w2[n] = fr == 0 ? c14 : c15; }
;                     } else { w1[0] = w1[1] = w2[0] = w2[1] = (f32x4){0.f, 0.f, 0.f, 0.f}; }
;                 } else {
; #pragma unroll
;                     for (int n = 0; n < 2; ++n)
; #pragma unroll
;                         for (int i = 0; i < 4; ++i) { const float ap = acc[ai][0][m - 1][n][i]; w1[n][i] = dppf<0x10F>(ap); w2[n][i] = dppf<0x10E>(ap); }
;                 }
;                 f32x4 hv[2];
; #pragma unroll
;                 for (int n = 0; n < 2; ++n) {
;                     const f32x4 a = acc[ai][0][m][n], b = acc[ai][1][m][n];
; #pragma unroll
;                     for (int i = 0; i < 4; ++i) {
;                         const float s1 = dppf<0x111>(a[i]), s2 = dppf<0x112>(a[i]);
;                         const float p1 = fr >= 1 ? s1 : w1[n][i], p2 = fr >= 2 ? s2 : w2[n][i];
;                         const float ac = cw0[n][i] * p2 + cw1[n][i] * p1 + cw2[n][i] * a[i] + cb[n][i];
;                         hv[n][i] = gelu_tanh(ac) * b[i];
;                     }
;                 }
;                 *(u32x4*)(hh + (size_t)row * DFF + cgc) = pack8(hv[0], hv[1]);
;                 if (samp) {
;                     if (fr >= 14) { const int bs = (row - MP) >> 4; float* p = out + O_CVS + ((size_t)bs * 2 + (fr - 14)) * DFF + cgc; *(f32x4*)p = acc[ai][0][m][0]; *(f32x4*)(p + 4) = acc[ai][0][m][1]; }
	v_fma_f32 v214, v66, v86, v74
	v_fma_f32 v215, v67, v87, v75
	v_fmac_f32_dpp v214, v86, v50 row_shr:1 row_mask:0xf bank_mask:0xf
	v_fmac_f32_dpp v215, v87, v51 row_shr:1 row_mask:0xf bank_mask:0xf
	v_fmac_f32_dpp v214, v162, v50 row_shl:15 row_mask:0xf bank_mask:0xf
	v_fmac_f32_dpp v215, v163, v51 row_shl:15 row_mask:0xf bank_mask:0xf
	v_fmac_f32_dpp v214, v86, v42 row_shr:2 row_mask:0xf bank_mask:0xf
	v_fmac_f32_dpp v215, v87, v43 row_shr:2 row_mask:0xf bank_mask:0xf
	v_fmac_f32_dpp v214, v162, v42 row_shl:14 row_mask:0xf bank_mask:0xf
	v_fmac_f32_dpp v215, v163, v43 row_shl:14 row_mask:0xf bank_mask:0xf
	v_mul_f32_e32 v216, 0x3d372713, v214
	v_mul_f32_e32 v217, 0x3d372713, v215
	v_mul_f32_e32 v218, 0x3fcc422a, v214
	v_mul_f32_e32 v219, 0x3fcc422a, v215
	v_fma_f32 v216, v214, v216, 1.0
	v_fma_f32 v217, v215, v217, 1.0
	v_mul_f32_e64 v218, v218, -v216
	v_mul_f32_e64 v219, v219, -v217
	v_mul_f32_e32 v218, 0x3fb8aa3b, v218
	v_mul_f32_e32 v219, 0x3fb8aa3b, v219
	v_exp_f32_e32 v218, v218
	v_exp_f32_e32 v219, v219
	v_add_f32_e32 v218, 1.0, v218
	v_add_f32_e32 v219, 1.0, v219
	v_rcp_f32_e32 v218, v218
	v_rcp_f32_e32 v219, v219
	v_mul_f32_e32 v216, v214, v218
	v_mul_f32_e32 v217, v215, v219
	v_mul_f32_e32 v94, v94, v216
	v_mul_f32_e32 v95, v95, v217
	v_fma_f32 v214, v68, v88, v76
	v_fma_f32 v215, v69, v89, v77
	v_fmac_f32_dpp v214, v88, v52 row_shr:1 row_mask:0xf bank_mask:0xf
	v_fmac_f32_dpp v215, v89, v53 row_shr:1 row_mask:0xf bank_mask:0xf
	v_fmac_f32_dpp v214, v164, v52 row_shl:15 row_mask:0xf bank_mask:0xf
	v_fmac_f32_dpp v215, v165, v53 row_shl:15 row_mask:0xf bank_mask:0xf
	v_fmac_f32_dpp v214, v88, v44 row_shr:2 row_mask:0xf bank_mask:0xf
	v_fmac_f32_dpp v215, v89, v45 row_shr:2 row_mask:0xf bank_mask:0xf
	v_fmac_f32_dpp v214, v164, v44 row_shl:14 row_mask:0xf bank_mask:0xf
	v_fmac_f32_dpp v215, v165, v45 row_shl:14 row_mask:0xf bank_mask:0xf
	v_mul_f32_e32 v216, 0x3d372713, v214
	v_mul_f32_e32 v217, 0x3d372713, v215
	v_mul_f32_e32 v218, 0x3fcc422a, v214
	v_mul_f32_e32 v219, 0x3fcc422a, v215
	v_fma_f32 v216, v214, v216, 1.0
	v_fma_f32 v217, v215, v217, 1.0
	v_mul_f32_e64 v218, v218, -v216
	v_mul_f32_e64 v219, v219, -v217
	v_mul_f32_e32 v218, 0x3fb8aa3b, v218
	v_mul_f32_e32 v219, 0x3fb8aa3b, v219
	v_exp_f32_e32 v218, v218
	v_exp_f32_e32 v219, v219
	v_add_f32_e32 v218, 1.0, v218
	v_add_f32_e32 v219, 1.0, v219
	v_rcp_f32_e32 v218, v218
	v_rcp_f32_e32 v219, v219
	v_mul_f32_e32 v216, v214, v218
	v_mul_f32_e32 v217, v215, v219
	v_mul_f32_e32 v96, v96, v216
	v_mul_f32_e32 v97, v97, v217
	v_fma_f32 v214, v70, v82, v78
	v_fma_f32 v215, v71, v83, v79
	v_fmac_f32_dpp v214, v82, v54 row_shr:1 row_mask:0xf bank_mask:0xf
	v_fmac_f32_dpp v215, v83, v55 row_shr:1 row_mask:0xf bank_mask:0xf
	v_fmac_f32_dpp v214, v166, v54 row_shl:15 row_mask:0xf bank_mask:0xf
	v_fmac_f32_dpp v215, v167, v55 row_shl:15 row_mask:0xf bank_mask:0xf
	v_fmac_f32_dpp v214, v82, v46 row_shr:2 row_mask:0xf bank_mask:0xf
	v_fmac_f32_dpp v215, v83, v47 row_shr:2 row_mask:0xf bank_mask:0xf
	v_fmac_f32_dpp v214, v166, v46 row_shl:14 row_mask:0xf bank_mask:0xf
	v_fmac_f32_dpp v215, v167, v47 row_shl:14 row_mask:0xf bank_mask:0xf
	v_mul_f32_e32 v216, 0x3d372713, v214
	v_mul_f32_e32 v217, 0x3d372713, v215
	v_mul_f32_e32 v218, 0x3fcc422a, v214
	v_mul_f32_e32 v219, 0x3fcc422a, v215
	v_fma_f32 v216, v214, v216, 1.0
	v_fma_f32 v217, v215, v217, 1.0
	v_mul_f32_e64 v218, v218, -v216
	v_mul_f32_e64 v219, v219, -v217
	v_mul_f32_e32 v218, 0x3fb8aa3b, v218
	v_mul_f32_e32 v219, 0x3fb8aa3b, v219
	v_exp_f32_e32 v218, v218
	v_exp_f32_e32 v219, v219
	v_add_f32_e32 v218, 1.0, v218
	v_add_f32_e32 v219, 1.0, v219
	v_rcp_f32_e32 v218, v218
	v_rcp_f32_e32 v219, v219
	v_mul_f32_e32 v216, v214, v218
	v_mul_f32_e32 v217, v215, v219
	v_mul_f32_e32 v90, v90, v216
	v_mul_f32_e32 v91, v91, v217
	v_fma_f32 v214, v72, v84, v80
	v_fma_f32 v215, v73, v85, v81
	v_fmac_f32_dpp v214, v84, v56 row_shr:1 row_mask:0xf bank_mask:0xf
	v_fmac_f32_dpp v215, v85, v57 row_shr:1 row_mask:0xf bank_mask:0xf
	v_fmac_f32_dpp v214, v168, v56 row_shl:15 row_mask:0xf bank_mask:0xf
	v_fmac_f32_dpp v215, v169, v57 row_shl:15 row_mask:0xf bank_mask:0xf
	v_fmac_f32_dpp v214, v84, v48 row_shr:2 row_mask:0xf bank_mask:0xf
	v_fmac_f32_dpp v215, v85, v49 row_shr:2 row_mask:0xf bank_mask:0xf
	v_fmac_f32_dpp v214, v168, v48 row_shl:14 row_mask:0xf bank_mask:0xf
	v_fmac_f32_dpp v215, v169, v49 row_shl:14 row_mask:0xf bank_mask:0xf
	v_mul_f32_e32 v216, 0x3d372713, v214
	v_mul_f32_e32 v217, 0x3d372713, v215
	v_mul_f32_e32 v218, 0x3fcc422a, v214
	v_mul_f32_e32 v219, 0x3fcc422a, v215
	v_fma_f32 v216, v214, v216, 1.0
	v_fma_f32 v217, v215, v217, 1.0
	v_mul_f32_e64 v218, v218, -v216
	v_mul_f32_e64 v219, v219, -v217
	v_mul_f32_e32 v218, 0x3fb8aa3b, v218
	v_mul_f32_e32 v219, 0x3fb8aa3b, v219
	v_exp_f32_e32 v218, v218
	v_exp_f32_e32 v219, v219
	v_add_f32_e32 v218, 1.0, v218
	v_add_f32_e32 v219, 1.0, v219
	v_rcp_f32_e32 v218, v218
	v_rcp_f32_e32 v219, v219
	v_mul_f32_e32 v216, v214, v218
	v_mul_f32_e32 v217, v215, v219
	v_mul_f32_e32 v92, v92, v216
	v_mul_f32_e32 v93, v93, v217
	v_cvt_pk_bf16_f32 v94, v94, v95
	v_cvt_pk_bf16_f32 v95, v96, v97
	v_cvt_pk_bf16_f32 v96, v90, v91
	v_cvt_pk_bf16_f32 v97, v92, v93
	v_add_u32_e32 v222, 0x200000, v195
	global_store_dwordx4 v222, v[94:97], s[70:71]
	s_add_u32 s86, s74, 0x90000
	s_addc_u32 s87, s75, 0
	global_load_dwordx4 v[162:165], v196, s[86:87]
	global_load_dwordx4 v[166:169], v196, s[86:87] offset:16
	s_add_u32 s86, s72, 0x90000
	s_addc_u32 s87, s73, 0
	s_mov_b32 exec_lo, 0xc000c000
	s_mov_b32 exec_hi, 0xc000c000
	global_store_dwordx4 v196, v[38:41], s[86:87]
	global_store_dwordx4 v196, v[34:37], s[86:87] offset:16
	s_mov_b64 exec, -1
	s_waitcnt vmcnt(2)
; #define PG8_LAS __attribute__((address_space(3)))
;     __device__ __forceinline__ void operator()(const f32x4 (&acc)[2][2][4][2], const Unit& u, int wr, int wc, int fr, int fq) const {
;     ...
;                 if (samp) {
;                     const int bs = (row - MP) >> 4;
; #pragma unroll
;                     for (int n = 0; n < 2; ++n) { const f32x4 s0 = *(const f32x4*)(state + ((size_t)bs * 2 + 0) * DFF + cgc + 4 * n), s1 = *(const f32x4*)(state + ((size_t)bs * 2 + 1) * DFF + cgc + 4 * n);
;                         w1[n] = s1; w2[n] = fr == 0 ? s0 : s1; }
;                 } else if (m == 0) {
;                     if (blk > 0) {
; #pragma unroll
;                         for (int n = 0; n < 2; ++n) { const f32x4 c14 = *(const PG8_LAS f32x4*)(xbuf + ((blk - 1) * 2 + 0) * 128 + cl + 4 * n), c15 = *(const PG8_LAS f32x4*)(xbuf + ((blk - 1) * 2 + 1) * 128 + cl + 4 * n);
;                             w1[n] = c15; w2[n] = fr == 0 ? c14 : c15; }
;                     } else { w1[0] = w1[1] = w2[0] = w2[1] = (f32x4){0.f, 0.f, 0.f, 0.f}; }
;                 } else {
; #pragma unroll
;                     for (int n = 0; n < 2; ++n)
; #pragma unroll
;                         for (int i = 0; i < 4; ++i) { const float ap = acc[ai][0][m - 1][n][i]; w1[n][i] = dppf<0x10F>(ap); w2[n][i] = dppf<0x10E>(ap); }
;                 }
;                 f32x4 hv[2];
; #pragma unroll
;                 for (int n = 0; n < 2; ++n) {
;                     const f32x4 a = acc[ai][0][m][n], b = acc[ai][1][m][n];
; #pragma unroll
;                     for (int i = 0; i < 4; ++i) {
;                         const float s1 = dppf<0x111>(a[i]), s2 = dppf<0x112>(a[i]);
;                         const float p1 = fr >= 1 ? s1 : w1[n][i], p2 = fr >= 2 ? s2 : w2[n][i];
;                         const float ac = cw0[n][i] * p2 + cw1[n][i] * p1 + cw2[n][i] * a[i] + cb[n][i];
;                         hv[n][i] = gelu_tanh(ac) * b[i];
;                     }
;                 }
;                 *(u32x4*)(hh + (size_t)row * DFF + cgc) = pack8(hv[0], hv[1]);
;                 if (samp) {
;                     if (fr >= 14) { const int bs = (row - MP) >> 4; float* p = out + O_CVS + ((size_t)bs * 2 + (fr - 14)) * DFF + cgc; *(f32x4*)p = acc[ai][0][m][0]; *(f32x4*)(p + 4) = acc[ai][0][m][1]; }
	v_fma_f32 v214, v66, v38, v74
	v_fma_f32 v215, v67, v39, v75
	v_fmac_f32_dpp v214, v38, v50 row_shr:1 row_mask:0xf bank_mask:0xf
	v_fmac_f32_dpp v215, v39, v51 row_shr:1 row_mask:0xf bank_mask:0xf
	v_fmac_f32_dpp v214, v162, v50 row_shl:15 row_mask:0xf bank_mask:0xf
	v_fmac_f32_dpp v215, v163, v51 row_shl:15 row_mask:0xf bank_mask:0xf
	v_fmac_f32_dpp v214, v38, v42 row_shr:2 row_mask:0xf bank_mask:0xf
	v_fmac_f32_dpp v215, v39, v43 row_shr:2 row_mask:0xf bank_mask:0xf
	v_fmac_f32_dpp v214, v162, v42 row_shl:14 row_mask:0xf bank_mask:0xf
	v_fmac_f32_dpp v215, v163, v43 row_shl:14 row_mask:0xf bank_mask:0xf
	v_mul_f32_e32 v216, 0x3d372713, v214
	v_mul_f32_e32 v217, 0x3d372713, v215
	v_mul_f32_e32 v218, 0x3fcc422a, v214
	v_mul_f32_e32 v219, 0x3fcc422a, v215
	v_fma_f32 v216, v214, v216, 1.0
	v_fma_f32 v217, v215, v217, 1.0
	v_mul_f32_e64 v218, v218, -v216
	v_mul_f32_e64 v219, v219, -v217
	v_mul_f32_e32 v218, 0x3fb8aa3b, v218
	v_mul_f32_e32 v219, 0x3fb8aa3b, v219
	v_exp_f32_e32 v218, v218
	v_exp_f32_e32 v219, v219
	v_add_f32_e32 v218, 1.0, v218
	v_add_f32_e32 v219, 1.0, v219
	v_rcp_f32_e32 v218, v218
	v_rcp_f32_e32 v219, v219
	v_mul_f32_e32 v216, v214, v218
	v_mul_f32_e32 v217, v215, v219
	v_mul_f32_e32 v62, v62, v216
	v_mul_f32_e32 v63, v63, v217
	v_fma_f32 v214, v68, v40, v76
	v_fma_f32 v215, v69, v41, v77
	v_fmac_f32_dpp v214, v40, v52 row_shr:1 row_mask:0xf bank_mask:0xf
	v_fmac_f32_dpp v215, v41, v53 row_shr:1 row_mask:0xf bank_mask:0xf
	v_fmac_f32_dpp v214, v164, v52 row_shl:15 row_mask:0xf bank_mask:0xf
	v_fmac_f32_dpp v215, v165, v53 row_shl:15 row_mask:0xf bank_mask:0xf
	v_fmac_f32_dpp v214, v40, v44 row_shr:2 row_mask:0xf bank_mask:0xf
	v_fmac_f32_dpp v215, v41, v45 row_shr:2 row_mask:0xf bank_mask:0xf
	v_fmac_f32_dpp v214, v164, v44 row_shl:14 row_mask:0xf bank_mask:0xf
	v_fmac_f32_dpp v215, v165, v45 row_shl:14 row_mask:0xf bank_mask:0xf
	v_mul_f32_e32 v216, 0x3d372713, v214
	v_mul_f32_e32 v217, 0x3d372713, v215
	v_mul_f32_e32 v218, 0x3fcc422a, v214
	v_mul_f32_e32 v219, 0x3fcc422a, v215
	v_fma_f32 v216, v214, v216, 1.0
	v_fma_f32 v217, v215, v217, 1.0
	v_mul_f32_e64 v218, v218, -v216
	v_mul_f32_e64 v219, v219, -v217
	v_mul_f32_e32 v218, 0x3fb8aa3b, v218
	v_mul_f32_e32 v219, 0x3fb8aa3b, v219
	v_exp_f32_e32 v218, v218
	v_exp_f32_e32 v219, v219
	v_add_f32_e32 v218, 1.0, v218
	v_add_f32_e32 v219, 1.0, v219
	v_rcp_f32_e32 v218, v218
	v_rcp_f32_e32 v219, v219
	v_mul_f32_e32 v216, v214, v218
	v_mul_f32_e32 v217, v215, v219
	v_mul_f32_e32 v64, v64, v216
	v_mul_f32_e32 v65, v65, v217
	v_fma_f32 v214, v70, v34, v78
	v_fma_f32 v215, v71, v35, v79
	v_fmac_f32_dpp v214, v34, v54 row_shr:1 row_mask:0xf bank_mask:0xf
	v_fmac_f32_dpp v215, v35, v55 row_shr:1 row_mask:0xf bank_mask:0xf
	v_fmac_f32_dpp v214, v166, v54 row_shl:15 row_mask:0xf bank_mask:0xf
	v_fmac_f32_dpp v215, v167, v55 row_shl:15 row_mask:0xf bank_mask:0xf
	v_fmac_f32_dpp v214, v34, v46 row_shr:2 row_mask:0xf bank_mask:0xf
	v_fmac_f32_dpp v215, v35, v47 row_shr:2 row_mask:0xf bank_mask:0xf
	v_fmac_f32_dpp v214, v166, v46 row_shl:14 row_mask:0xf bank_mask:0xf
	v_fmac_f32_dpp v215, v167, v47 row_shl:14 row_mask:0xf bank_mask:0xf
	v_mul_f32_e32 v216, 0x3d372713, v214
	v_mul_f32_e32 v217, 0x3d372713, v215
	v_mul_f32_e32 v218, 0x3fcc422a, v214
	v_mul_f32_e32 v219, 0x3fcc422a, v215
	v_fma_f32 v216, v214, v216, 1.0
	v_fma_f32 v217, v215, v217, 1.0
	v_mul_f32_e64 v218, v218, -v216
	v_mul_f32_e64 v219, v219, -v217
	v_mul_f32_e32 v218, 0x3fb8aa3b, v218
	v_mul_f32_e32 v219, 0x3fb8aa3b, v219
	v_exp_f32_e32 v218, v218
	v_exp_f32_e32 v219, v219
	v_add_f32_e32 v218, 1.0, v218
	v_add_f32_e32 v219, 1.0, v219
	v_rcp_f32_e32 v218, v218
	v_rcp_f32_e32 v219, v219
	v_mul_f32_e32 v216, v214, v218
	v_mul_f32_e32 v217, v215, v219
	v_mul_f32_e32 v58, v58, v216
	v_mul_f32_e32 v59, v59, v217
	v_fma_f32 v214, v72, v36, v80
	v_fma_f32 v215, v73, v37, v81
	v_fmac_f32_dpp v214, v36, v56 row_shr:1 row_mask:0xf bank_mask:0xf
	v_fmac_f32_dpp v215, v37, v57 row_shr:1 row_mask:0xf bank_mask:0xf
	v_fmac_f32_dpp v214, v168, v56 row_shl:15 row_mask:0xf bank_mask:0xf
	v_fmac_f32_dpp v215, v169, v57 row_shl:15 row_mask:0xf bank_mask:0xf
	v_fmac_f32_dpp v214, v36, v48 row_shr:2 row_mask:0xf bank_mask:0xf
	v_fmac_f32_dpp v215, v37, v49 row_shr:2 row_mask:0xf bank_mask:0xf
	v_fmac_f32_dpp v214, v168, v48 row_shl:14 row_mask:0xf bank_mask:0xf
	v_fmac_f32_dpp v215, v169, v49 row_shl:14 row_mask:0xf bank_mask:0xf
	v_mul_f32_e32 v216, 0x3d372713, v214
	v_mul_f32_e32 v217, 0x3d372713, v215
	v_mul_f32_e32 v218, 0x3fcc422a, v214
	v_mul_f32_e32 v219, 0x3fcc422a, v215
	v_fma_f32 v216, v214, v216, 1.0
	v_fma_f32 v217, v215, v217, 1.0
	v_mul_f32_e64 v218, v218, -v216
	v_mul_f32_e64 v219, v219, -v217
	v_mul_f32_e32 v218, 0x3fb8aa3b, v218
	v_mul_f32_e32 v219, 0x3fb8aa3b, v219
	v_exp_f32_e32 v218, v218
	v_exp_f32_e32 v219, v219
	v_add_f32_e32 v218, 1.0, v218
	v_add_f32_e32 v219, 1.0, v219
	v_rcp_f32_e32 v218, v218
	v_rcp_f32_e32 v219, v219
	v_mul_f32_e32 v216, v214, v218
	v_mul_f32_e32 v217, v215, v219
	v_mul_f32_e32 v60, v60, v216
	v_mul_f32_e32 v61, v61, v217
	v_cvt_pk_bf16_f32 v62, v62, v63
	v_cvt_pk_bf16_f32 v63, v64, v65
	v_cvt_pk_bf16_f32 v64, v58, v59
	v_cvt_pk_bf16_f32 v65, v60, v61
	v_add_u32_e32 v222, 0x240000, v195
	global_store_dwordx4 v222, v[62:65], s[70:71]
	s_add_u32 s86, s74, 0xa0000
	s_addc_u32 s87, s75, 0
	global_load_dwordx4 v[162:165], v196, s[86:87]
	global_load_dwordx4 v[166:169], v196, s[86:87] offset:16
	s_add_u32 s86, s72, 0xa0000
	s_addc_u32 s87, s73, 0
	s_mov_b32 exec_lo, 0xc000c000
	s_mov_b32 exec_hi, 0xc000c000
	global_store_dwordx4 v196, v[22:25], s[86:87]
	global_store_dwordx4 v196, v[18:21], s[86:87] offset:16
	s_mov_b64 exec, -1
	s_waitcnt vmcnt(2)
; #define PG8_LAS __attribute__((address_space(3)))
;     __device__ __forceinline__ void operator()(const f32x4 (&acc)[2][2][4][2], const Unit& u, int wr, int wc, int fr, int fq) const {
;     ...
;                 if (samp) {
;                     const int bs = (row - MP) >> 4;
; #pragma unroll
;                     for (int n = 0; n < 2; ++n) { const f32x4 s0 = *(const f32x4*)(state + ((size_t)bs * 2 + 0) * DFF + cgc + 4 * n), s1 = *(const f32x4*)(state + ((size_t)bs * 2 + 1) * DFF + cgc + 4 * n);
;                         w1[n] = s1; w2[n] = fr == 0 ? s0 : s1; }
;                 } else if (m == 0) {
;                     if (blk > 0) {
; #pragma unroll
;                         for (int n = 0; n < 2; ++n) { const f32x4 c14 = *(const PG8_LAS f32x4*)(xbuf + ((blk - 1) * 2 + 0) * 128 + cl + 4 * n), c15 = *(const PG8_LAS f32x4*)(xbuf + ((blk - 1) * 2 + 1) * 128 + cl + 4 * n);
;                             w1[n] = c15; w2[n] = fr == 0 ? c14 : c15; }
;                     } else { w1[0] = w1[1] = w2[0] = w2[1] = (f32x4){0.f, 0.f, 0.f, 0.f}; }
;                 } else {
; #pragma unroll
;                     for (int n = 0; n < 2; ++n)
; #pragma unroll
;                         for (int i = 0; i < 4; ++i) { const float ap = acc[ai][0][m - 1][n][i]; w1[n][i] = dppf<0x10F>(ap); w2[n][i] = dppf<0x10E>(ap); }
;                 }
;                 f32x4 hv[2];
; #pragma unroll
;                 for (int n = 0; n < 2; ++n) {
;                     const f32x4 a = acc[ai][0][m][n], b = acc[ai][1][m][n];
; #pragma unroll
;                     for (int i = 0; i < 4; ++i) {
;                         const float s1 = dppf<0x111>(a[i]), s2 = dppf<0x112>(a[i]);
;                         const float p1 = fr >= 1 ? s1 : w1[n][i], p2 = fr >= 2 ? s2 : w2[n][i];
;                         const float ac = cw0[n][i] * p2 + cw1[n][i] * p1 + cw2[n][i] * a[i] + cb[n][i];
;                         hv[n][i] = gelu_tanh(ac) * b[i];
;                     }
;                 }
;                 *(u32x4*)(hh + (size_t)row * DFF + cgc) = pack8(hv[0], hv[1]);
;                 if (samp) {
;                     if (fr >= 14) { const int bs = (row - MP) >> 4; float* p = out + O_CVS + ((size_t)bs * 2 + (fr - 14)) * DFF + cgc; *(f32x4*)p = acc[ai][0][m][0]; *(f32x4*)(p + 4) = acc[ai][0][m][1]; }
	v_fma_f32 v214, v66, v22, v74
	v_fma_f32 v215, v67, v23, v75
	v_fmac_f32_dpp v214, v22, v50 row_shr:1 row_mask:0xf bank_mask:0xf
	v_fmac_f32_dpp v215, v23, v51 row_shr:1 row_mask:0xf bank_mask:0xf
	v_fmac_f32_dpp v214, v162, v50 row_shl:15 row_mask:0xf bank_mask:0xf
	v_fmac_f32_dpp v215, v163, v51 row_shl:15 row_mask:0xf bank_mask:0xf
	v_fmac_f32_dpp v214, v22, v42 row_shr:2 row_mask:0xf bank_mask:0xf
	v_fmac_f32_dpp v215, v23, v43 row_shr:2 row_mask:0xf bank_mask:0xf
	v_fmac_f32_dpp v214, v162, v42 row_shl:14 row_mask:0xf bank_mask:0xf
	v_fmac_f32_dpp v215, v163, v43 row_shl:14 row_mask:0xf bank_mask:0xf
	v_mul_f32_e32 v216, 0x3d372713, v214
	v_mul_f32_e32 v217, 0x3d372713, v215
	v_mul_f32_e32 v218, 0x3fcc422a, v214
	v_mul_f32_e32 v219, 0x3fcc422a, v215
	v_fma_f32 v216, v214, v216, 1.0
	v_fma_f32 v217, v215, v217, 1.0
	v_mul_f32_e64 v218, v218, -v216
	v_mul_f32_e64 v219, v219, -v217
	v_mul_f32_e32 v218, 0x3fb8aa3b, v218
	v_mul_f32_e32 v219, 0x3fb8aa3b, v219
	v_exp_f32_e32 v218, v218
	v_exp_f32_e32 v219, v219
	v_add_f32_e32 v218, 1.0, v218
	v_add_f32_e32 v219, 1.0, v219
	v_rcp_f32_e32 v218, v218
	v_rcp_f32_e32 v219, v219
	v_mul_f32_e32 v216, v214, v218
	v_mul_f32_e32 v217, v215, v219
	v_mul_f32_e32 v30, v30, v216
	v_mul_f32_e32 v31, v31, v217
	v_fma_f32 v214, v68, v24, v76
	v_fma_f32 v215, v69, v25, v77
	v_fmac_f32_dpp v214, v24, v52 row_shr:1 row_mask:0xf bank_mask:0xf
	v_fmac_f32_dpp v215, v25, v53 row_shr:1 row_mask:0xf bank_mask:0xf
	v_fmac_f32_dpp v214, v164, v52 row_shl:15 row_mask:0xf bank_mask:0xf
	v_fmac_f32_dpp v215, v165, v53 row_shl:15 row_mask:0xf bank_mask:0xf
	v_fmac_f32_dpp v214, v24, v44 row_shr:2 row_mask:0xf bank_mask:0xf
	v_fmac_f32_dpp v215, v25, v45 row_shr:2 row_mask:0xf bank_mask:0xf
	v_fmac_f32_dpp v214, v164, v44 row_shl:14 row_mask:0xf bank_mask:0xf
	v_fmac_f32_dpp v215, v165, v45 row_shl:14 row_mask:0xf bank_mask:0xf
	v_mul_f32_e32 v216, 0x3d372713, v214
	v_mul_f32_e32 v217, 0x3d372713, v215
	v_mul_f32_e32 v218, 0x3fcc422a, v214
	v_mul_f32_e32 v219, 0x3fcc422a, v215
	v_fma_f32 v216, v214, v216, 1.0
	v_fma_f32 v217, v215, v217, 1.0
	v_mul_f32_e64 v218, v218, -v216
	v_mul_f32_e64 v219, v219, -v217
	v_mul_f32_e32 v218, 0x3fb8aa3b, v218
	v_mul_f32_e32 v219, 0x3fb8aa3b, v219
	v_exp_f32_e32 v218, v218
	v_exp_f32_e32 v219, v219
	v_add_f32_e32 v218, 1.0, v218
	v_add_f32_e32 v219, 1.0, v219
	v_rcp_f32_e32 v218, v218
	v_rcp_f32_e32 v219, v219
	v_mul_f32_e32 v216, v214, v218
	v_mul_f32_e32 v217, v215, v219
	v_mul_f32_e32 v32, v32, v216
	v_mul_f32_e32 v33, v33, v217
	v_fma_f32 v214, v70, v18, v78
	v_fma_f32 v215, v71, v19, v79
	v_fmac_f32_dpp v214, v18, v54 row_shr:1 row_mask:0xf bank_mask:0xf
	v_fmac_f32_dpp v215, v19, v55 row_shr:1 row_mask:0xf bank_mask:0xf
	v_fmac_f32_dpp v214, v166, v54 row_shl:15 row_mask:0xf bank_mask:0xf
	v_fmac_f32_dpp v215, v167, v55 row_shl:15 row_mask:0xf bank_mask:0xf
	v_fmac_f32_dpp v214, v18, v46 row_shr:2 row_mask:0xf bank_mask:0xf
	v_fmac_f32_dpp v215, v19, v47 row_shr:2 row_mask:0xf bank_mask:0xf
	v_fmac_f32_dpp v214, v166, v46 row_shl:14 row_mask:0xf bank_mask:0xf
	v_fmac_f32_dpp v215, v167, v47 row_shl:14 row_mask:0xf bank_mask:0xf
	v_mul_f32_e32 v216, 0x3d372713, v214
	v_mul_f32_e32 v217, 0x3d372713, v215
	v_mul_f32_e32 v218, 0x3fcc422a, v214
	v_mul_f32_e32 v219, 0x3fcc422a, v215
	v_fma_f32 v216, v214, v216, 1.0
	v_fma_f32 v217, v215, v217, 1.0
	v_mul_f32_e64 v218, v218, -v216
	v_mul_f32_e64 v219, v219, -v217
	v_mul_f32_e32 v218, 0x3fb8aa3b, v218
	v_mul_f32_e32 v219, 0x3fb8aa3b, v219
	v_exp_f32_e32 v218, v218
	v_exp_f32_e32 v219, v219
	v_add_f32_e32 v218, 1.0, v218
	v_add_f32_e32 v219, 1.0, v219
	v_rcp_f32_e32 v218, v218
	v_rcp_f32_e32 v219, v219
	v_mul_f32_e32 v216, v214, v218
	v_mul_f32_e32 v217, v215, v219
	v_mul_f32_e32 v26, v26, v216
	v_mul_f32_e32 v27, v27, v217
	v_fma_f32 v214, v72, v20, v80
	v_fma_f32 v215, v73, v21, v81
	v_fmac_f32_dpp v214, v20, v56 row_shr:1 row_mask:0xf bank_mask:0xf
	v_fmac_f32_dpp v215, v21, v57 row_shr:1 row_mask:0xf bank_mask:0xf
	v_fmac_f32_dpp v214, v168, v56 row_shl:15 row_mask:0xf bank_mask:0xf
	v_fmac_f32_dpp v215, v169, v57 row_shl:15 row_mask:0xf bank_mask:0xf
	v_fmac_f32_dpp v214, v20, v48 row_shr:2 row_mask:0xf bank_mask:0xf
	v_fmac_f32_dpp v215, v21, v49 row_shr:2 row_mask:0xf bank_mask:0xf
	v_fmac_f32_dpp v214, v168, v48 row_shl:14 row_mask:0xf bank_mask:0xf
	v_fmac_f32_dpp v215, v169, v49 row_shl:14 row_mask:0xf bank_mask:0xf
	v_mul_f32_e32 v216, 0x3d372713, v214
	v_mul_f32_e32 v217, 0x3d372713, v215
	v_mul_f32_e32 v218, 0x3fcc422a, v214
	v_mul_f32_e32 v219, 0x3fcc422a, v215
	v_fma_f32 v216, v214, v216, 1.0
	v_fma_f32 v217, v215, v217, 1.0
	v_mul_f32_e64 v218, v218, -v216
	v_mul_f32_e64 v219, v219, -v217
	v_mul_f32_e32 v218, 0x3fb8aa3b, v218
	v_mul_f32_e32 v219, 0x3fb8aa3b, v219
	v_exp_f32_e32 v218, v218
	v_exp_f32_e32 v219, v219
	v_add_f32_e32 v218, 1.0, v218
	v_add_f32_e32 v219, 1.0, v219
	v_rcp_f32_e32 v218, v218
	v_rcp_f32_e32 v219, v219
	v_mul_f32_e32 v216, v214, v218
	v_mul_f32_e32 v217, v215, v219
	v_mul_f32_e32 v28, v28, v216
	v_mul_f32_e32 v29, v29, v217
	v_cvt_pk_bf16_f32 v30, v30, v31
	v_cvt_pk_bf16_f32 v31, v32, v33
	v_cvt_pk_bf16_f32 v32, v26, v27
	v_cvt_pk_bf16_f32 v33, v28, v29
	v_add_u32_e32 v222, 0x280000, v195
	global_store_dwordx4 v222, v[30:33], s[70:71]
	s_add_u32 s86, s74, 0xb0000
	s_addc_u32 s87, s75, 0
	global_load_dwordx4 v[162:165], v196, s[86:87]
	global_load_dwordx4 v[166:169], v196, s[86:87] offset:16
	s_add_u32 s86, s72, 0xb0000
	s_addc_u32 s87, s73, 0
	s_mov_b32 exec_lo, 0xc000c000
	s_mov_b32 exec_hi, 0xc000c000
	global_store_dwordx4 v196, v[6:9], s[86:87]
	global_store_dwordx4 v196, v[2:5], s[86:87] offset:16
	s_mov_b64 exec, -1
	s_waitcnt vmcnt(2)
; __device__ __forceinline__ u32x4 pack8(const f32x4 a, const f32x4 b) { u32x4 w; w.x = cvt_pk_bf16(a[0], a[1]); w.y = cvt_pk_bf16(a[2], a[3]); w.z = cvt_pk_bf16(b[0], b[1]); w.w = cvt_pk_bf16(b[2], b[3]); return w; }
; template <int CTRL> __device__ __forceinline__ float dppf(float v) { return __builtin_bit_cast(float, __builtin_amdgcn_update_dpp(0, __builtin_bit_cast(int, v), CTRL, 0xf, 0xf, true)); }
; __device__ __forceinline__ float gelu_tanh(float x) {
;     const float u2 = 1.5957691216057308f * x * (1.0f + 0.044715f * x * x);
;     return x * __builtin_amdgcn_rcpf(1.0f + __builtin_amdgcn_exp2f(-u2 * LOG2E));
; }
;     __device__ __forceinline__ void operator()(const f32x4 (&acc)[2][2][4][2], const Unit& u, int wr, int wc, int fr, int fq) const {
;     ...
;                 f32x4 hv[2];
; #pragma unroll
;                 for (int n = 0; n < 2; ++n) {
;                     const f32x4 a = acc[ai][0][m][n], b = acc[ai][1][m][n];
; #pragma unroll
;                     for (int i = 0; i < 4; ++i) {
;                         const float s1 = dppf<0x111>(a[i]), s2 = dppf<0x112>(a[i]);
;                         const float p1 = fr >= 1 ? s1 : w1[n][i], p2 = fr >= 2 ? s2 : w2[n][i];
;                         const float ac = cw0[n][i] * p2 + cw1[n][i] * p1 + cw2[n][i] * a[i] + cb[n][i];
;                         hv[n][i] = gelu_tanh(ac) * b[i];
;                     }
;                 }
;                 *(u32x4*)(hh + (size_t)row * DFF + cgc) = pack8(hv[0], hv[1]);
	v_fma_f32 v214, v66, v6, v74
	v_fma_f32 v215, v67, v7, v75
	v_fmac_f32_dpp v214, v6, v50 row_shr:1 row_mask:0xf bank_mask:0xf
	v_fmac_f32_dpp v215, v7, v51 row_shr:1 row_mask:0xf bank_mask:0xf
	v_fmac_f32_dpp v214, v162, v50 row_shl:15 row_mask:0xf bank_mask:0xf
	v_fmac_f32_dpp v215, v163, v51 row_shl:15 row_mask:0xf bank_mask:0xf
	v_fmac_f32_dpp v214, v6, v42 row_shr:2 row_mask:0xf bank_mask:0xf
	v_fmac_f32_dpp v215, v7, v43 row_shr:2 row_mask:0xf bank_mask:0xf
	v_fmac_f32_dpp v214, v162, v42 row_shl:14 row_mask:0xf bank_mask:0xf
	v_fmac_f32_dpp v215, v163, v43 row_shl:14 row_mask:0xf bank_mask:0xf
	v_mul_f32_e32 v216, 0x3d372713, v214
	v_mul_f32_e32 v217, 0x3d372713, v215
	v_mul_f32_e32 v218, 0x3fcc422a, v214
	v_mul_f32_e32 v219, 0x3fcc422a, v215
	v_fma_f32 v216, v214, v216, 1.0
	v_fma_f32 v217, v215, v217, 1.0
	v_mul_f32_e64 v218, v218, -v216
	v_mul_f32_e64 v219, v219, -v217
	v_mul_f32_e32 v218, 0x3fb8aa3b, v218
	v_mul_f32_e32 v219, 0x3fb8aa3b, v219
	v_exp_f32_e32 v218, v218
	v_exp_f32_e32 v219, v219
	v_add_f32_e32 v218, 1.0, v218
	v_add_f32_e32 v219, 1.0, v219
	v_rcp_f32_e32 v218, v218
	v_rcp_f32_e32 v219, v219
	v_mul_f32_e32 v216, v214, v218
	v_mul_f32_e32 v217, v215, v219
	v_mul_f32_e32 v14, v14, v216
	v_mul_f32_e32 v15, v15, v217
	v_fma_f32 v214, v68, v8, v76
	v_fma_f32 v215, v69, v9, v77
	v_fmac_f32_dpp v214, v8, v52 row_shr:1 row_mask:0xf bank_mask:0xf
	v_fmac_f32_dpp v215, v9, v53 row_shr:1 row_mask:0xf bank_mask:0xf
	v_fmac_f32_dpp v214, v164, v52 row_shl:15 row_mask:0xf bank_mask:0xf
	v_fmac_f32_dpp v215, v165, v53 row_shl:15 row_mask:0xf bank_mask:0xf
	v_fmac_f32_dpp v214, v8, v44 row_shr:2 row_mask:0xf bank_mask:0xf
	v_fmac_f32_dpp v215, v9, v45 row_shr:2 row_mask:0xf bank_mask:0xf
	v_fmac_f32_dpp v214, v164, v44 row_shl:14 row_mask:0xf bank_mask:0xf
	v_fmac_f32_dpp v215, v165, v45 row_shl:14 row_mask:0xf bank_mask:0xf
	v_mul_f32_e32 v216, 0x3d372713, v214
	v_mul_f32_e32 v217, 0x3d372713, v215
	v_mul_f32_e32 v218, 0x3fcc422a, v214
	v_mul_f32_e32 v219, 0x3fcc422a, v215
	v_fma_f32 v216, v214, v216, 1.0
	v_fma_f32 v217, v215, v217, 1.0
	v_mul_f32_e64 v218, v218, -v216
	v_mul_f32_e64 v219, v219, -v217
	v_mul_f32_e32 v218, 0x3fb8aa3b, v218
	v_mul_f32_e32 v219, 0x3fb8aa3b, v219
	v_exp_f32_e32 v218, v218
	v_exp_f32_e32 v219, v219
	v_add_f32_e32 v218, 1.0, v218
	v_add_f32_e32 v219, 1.0, v219
	v_rcp_f32_e32 v218, v218
	v_rcp_f32_e32 v219, v219
	v_mul_f32_e32 v216, v214, v218
	v_mul_f32_e32 v217, v215, v219
	v_mul_f32_e32 v16, v16, v216
	v_mul_f32_e32 v17, v17, v217
	v_fma_f32 v214, v70, v2, v78
	v_fma_f32 v215, v71, v3, v79
	v_fmac_f32_dpp v214, v2, v54 row_shr:1 row_mask:0xf bank_mask:0xf
	v_fmac_f32_dpp v215, v3, v55 row_shr:1 row_mask:0xf bank_mask:0xf
	v_fmac_f32_dpp v214, v166, v54 row_shl:15 row_mask:0xf bank_mask:0xf
	v_fmac_f32_dpp v215, v167, v55 row_shl:15 row_mask:0xf bank_mask:0xf
	v_fmac_f32_dpp v214, v2, v46 row_shr:2 row_mask:0xf bank_mask:0xf
	v_fmac_f32_dpp v215, v3, v47 row_shr:2 row_mask:0xf bank_mask:0xf
	v_fmac_f32_dpp v214, v166, v46 row_shl:14 row_mask:0xf bank_mask:0xf
	v_fmac_f32_dpp v215, v167, v47 row_shl:14 row_mask:0xf bank_mask:0xf
	v_mul_f32_e32 v216, 0x3d372713, v214
	v_mul_f32_e32 v217, 0x3d372713, v215
	v_mul_f32_e32 v218, 0x3fcc422a, v214
	v_mul_f32_e32 v219, 0x3fcc422a, v215
	v_fma_f32 v216, v214, v216, 1.0
	v_fma_f32 v217, v215, v217, 1.0
	v_mul_f32_e64 v218, v218, -v216
	v_mul_f32_e64 v219, v219, -v217
	v_mul_f32_e32 v218, 0x3fb8aa3b, v218
	v_mul_f32_e32 v219, 0x3fb8aa3b, v219
	v_exp_f32_e32 v218, v218
	v_exp_f32_e32 v219, v219
	v_add_f32_e32 v218, 1.0, v218
	v_add_f32_e32 v219, 1.0, v219
	v_rcp_f32_e32 v218, v218
	v_rcp_f32_e32 v219, v219
	v_mul_f32_e32 v216, v214, v218
	v_mul_f32_e32 v217, v215, v219
	v_mul_f32_e32 v10, v10, v216
	v_mul_f32_e32 v11, v11, v217
	v_fma_f32 v214, v72, v4, v80
	v_fma_f32 v215, v73, v5, v81
	v_fmac_f32_dpp v214, v4, v56 row_shr:1 row_mask:0xf bank_mask:0xf
	v_fmac_f32_dpp v215, v5, v57 row_shr:1 row_mask:0xf bank_mask:0xf
	v_fmac_f32_dpp v214, v168, v56 row_shl:15 row_mask:0xf bank_mask:0xf
	v_fmac_f32_dpp v215, v169, v57 row_shl:15 row_mask:0xf bank_mask:0xf
	v_fmac_f32_dpp v214, v4, v48 row_shr:2 row_mask:0xf bank_mask:0xf
	v_fmac_f32_dpp v215, v5, v49 row_shr:2 row_mask:0xf bank_mask:0xf
	v_fmac_f32_dpp v214, v168, v48 row_shl:14 row_mask:0xf bank_mask:0xf
	v_fmac_f32_dpp v215, v169, v49 row_shl:14 row_mask:0xf bank_mask:0xf
	v_mul_f32_e32 v216, 0x3d372713, v214
	v_mul_f32_e32 v217, 0x3d372713, v215
	v_mul_f32_e32 v218, 0x3fcc422a, v214
	v_mul_f32_e32 v219, 0x3fcc422a, v215
	v_fma_f32 v216, v214, v216, 1.0
	v_fma_f32 v217, v215, v217, 1.0
	v_mul_f32_e64 v218, v218, -v216
	v_mul_f32_e64 v219, v219, -v217
	v_mul_f32_e32 v218, 0x3fb8aa3b, v218
	v_mul_f32_e32 v219, 0x3fb8aa3b, v219
	v_exp_f32_e32 v218, v218
	v_exp_f32_e32 v219, v219
	v_add_f32_e32 v218, 1.0, v218
	v_add_f32_e32 v219, 1.0, v219
	v_rcp_f32_e32 v218, v218
	v_rcp_f32_e32 v219, v219
	v_mul_f32_e32 v216, v214, v218
	v_mul_f32_e32 v217, v215, v219
	v_mul_f32_e32 v12, v12, v216
	v_mul_f32_e32 v13, v13, v217
	v_cvt_pk_bf16_f32 v14, v14, v15
	v_cvt_pk_bf16_f32 v15, v16, v17
	v_cvt_pk_bf16_f32 v16, v10, v11
	v_cvt_pk_bf16_f32 v17, v12, v13
	v_add_u32_e32 v222, 0x2c0000, v195
	global_store_dwordx4 v222, v[14:17], s[70:71]
.Lup_exit:
	s_mov_b64 exec, -1
	v_readlane_b32 s68, v250, 6
	s_andn2_b64 vcc, exec, s[8:9]
	s_mov_b64 s[0:1], -1
	s_cbranch_vccnz .LBB0_1224
